# combo k=2 + phase B: workgroups with bid>=256 run attention items before their in-proj tile (MFMA/L2 vs VALU overlap)
# speedup vs baseline: 1.0121x; 1.0068x over previous
; __global__ void __launch_bounds__(256, 2) hybrid_megakernel(Params p) {
;     ...
;     for (int vb = bid; vb < 512; vb += nb) {
;       { const int q2 = vb >> 3; inproj_tile<4>(p, l, (vb & 7) * 16 + (q2 & 15), 8 + (q2 >> 4), lds); }
.LBB0_213:
	s_or_b64 exec, exec, s[0:1]
	v_readlane_b32 s0, v235, 23
	v_readlane_b32 s1, v235, 24
	s_andn2_b64 vcc, exec, s[0:1]
	s_waitcnt lgkmcnt(0)
	v_cndmask_b32_e64 v0, 0, 1, s[0:1]
	v_cmp_ne_u32_e64 s[2:3], 1, v0
	s_barrier
	s_nop 0
	v_writelane_b32 v234, s2, 27
	s_nop 1
	v_writelane_b32 v234, s3, 28
	s_cbranch_vccnz .LBB0_298
	v_readlane_b32 s0, v234, 24
	s_mul_i32 s28, s0, 0xd00
	s_lshl_b32 s29, s0, 1
	v_readlane_b32 s30, v234, 18
	v_readlane_b32 s31, v234, 17
	v_readlane_b32 s34, v234, 14
	v_readlane_b32 s35, v234, 13
	v_readlane_b32 s36, v235, 0
	s_nop 1
	s_lshr_b32 s98, s36, 8
	s_and_b32 s98, s98, 1
	s_branch .LBB0_217

; __global__ void __launch_bounds__(256, 2) hybrid_megakernel(Params p) {
;     ...
;     for (int vb = bid; vb < 512; vb += nb) {
;       { const int q2 = vb >> 3; inproj_tile<4>(p, l, (vb & 7) * 16 + (q2 & 15), 8 + (q2 >> 4), lds); }
.LBB0_216:
	s_cmp_eq_u32 s98, 1
	s_cbranch_scc0 .Lb_cont
	s_mov_b32 s98, 2
	s_branch .Lb_tile
.Lb_tile_late_done:
	s_mov_b32 s98, 1

; __global__ void __launch_bounds__(256, 2) hybrid_megakernel(Params p) {
;     ...
;     for (int vb = bid; vb < 512; vb += nb) {
;       { const int q2 = vb >> 3; inproj_tile<4>(p, l, (vb & 7) * 16 + (q2 & 15), 8 + (q2 >> 4), lds); }
;       if (vb < 64) cmp_item(p, l, vb, lds);
;       else {
;         const int j = vb - 64;
;         if (vb >= 256) { const int i2 = (vb - 256) >> 3; inproj_tile<2>(p, l, (vb & 7) * 16 + (i2 & 15), 24 + (i2 >> 4), lds); }
.LBB0_217:
	s_cmp_lg_u32 s98, 1
	s_cbranch_scc1 .Lb_tile
	s_lshl_b32 s0, s36, 4
	s_and_b32 s0, s0, 0x70
	s_bfe_u32 s1, s36, 0x40003
	s_or_b32 s4, s0, s1
	s_lshl_b32 s80, s4, 7
	s_lshl_b32 s26, s4, 18
	s_branch .Lb_items

; template <int NTW>
; DI void inproj_tile(const Params& p, int l, int mt, int ntile, char* lds) {
;     ...
; #pragma unroll 4
;   for (int i = 0; i < NCOLS / 16; ++i) {
;     const int c = tid + 256 * i, tl = c / (NCOLS / 8), ch = c % (NCOLS / 8);
;     const u32x4 v = *(const u32x4*)(lds + tl * RS + ch * 16);
;     *(u32x4*)(proj + ((size_t)mt * 128 + tl) * NP + ntile * NCOLS + ch * 8) = v;
;   }
; __global__ void __launch_bounds__(256, 2) hybrid_megakernel(Params p) {
;     ...
;     for (int vb = bid; vb < 512; vb += nb) {
;       { const int q2 = vb >> 3; inproj_tile<4>(p, l, (vb & 7) * 16 + (q2 & 15), 8 + (q2 >> 4), lds); }
;       if (vb < 64) cmp_item(p, l, vb, lds);
;       else {
;         const int j = vb - 64;
;         if (vb >= 256) { const int i2 = (vb - 256) >> 3; inproj_tile<2>(p, l, (vb & 7) * 16 + (i2 & 15), 24 + (i2 >> 4), lds); }
.LBB0_220:
	v_add_u32_e32 v10, s2, v181
	v_ashrrev_i32_e32 v0, 31, v10
	v_lshrrev_b32_e32 v0, 27, v0
	v_add_u32_e32 v0, v10, v0
	v_ashrrev_i32_e32 v4, 5, v0
	v_and_b32_e32 v0, 0xffffffe0, v0
	v_sub_u32_e32 v11, v10, v0
	v_mul_lo_u32 v0, v4, s73
	v_lshl_add_u32 v0, v11, 4, v0
	ds_read_b128 v[0:3], v0
	v_ashrrev_i32_e32 v5, 31, v4
	v_lshl_add_u64 v[4:5], v[4:5], 0, s[80:81]
	v_mov_b64_e32 v[6:7], s[0:1]
	v_mad_u64_u32 v[8:9], s[4:5], v4, s33, v[6:7]
	v_lshlrev_b32_e32 v4, 3, v11
	v_mad_i32_i24 v9, v5, s33, v9
	v_ashrrev_i32_e32 v5, 31, v4
	v_lshl_add_u64 v[4:5], v[4:5], 1, v[8:9]
	s_waitcnt lgkmcnt(0)
	global_store_dwordx4 v[4:5], v[0:3], off
	s_addk_i32 s2, 0x400
	s_cmpk_lg_i32 s2, 0x1000
	v_add_u32_e32 v0, 0x100, v10
	v_ashrrev_i32_e32 v1, 31, v0
	v_lshrrev_b32_e32 v1, 27, v1
	v_add_u32_e32 v1, v0, v1
	v_ashrrev_i32_e32 v4, 5, v1
	v_and_b32_e32 v1, 0xffffffe0, v1
	v_sub_u32_e32 v11, v0, v1
	v_mul_lo_u32 v0, v4, s73
	v_lshl_add_u32 v0, v11, 4, v0
	ds_read_b128 v[0:3], v0
	v_ashrrev_i32_e32 v5, 31, v4
	v_lshl_add_u64 v[4:5], v[4:5], 0, s[80:81]
	v_mad_u64_u32 v[8:9], s[4:5], v4, s33, v[6:7]
	v_lshlrev_b32_e32 v4, 3, v11
	v_mad_i32_i24 v9, v5, s33, v9
	v_ashrrev_i32_e32 v5, 31, v4
	v_lshl_add_u64 v[4:5], v[4:5], 1, v[8:9]
	s_waitcnt lgkmcnt(0)
	global_store_dwordx4 v[4:5], v[0:3], off
	s_nop 1
	v_add_u32_e32 v0, 0x200, v10
	v_ashrrev_i32_e32 v1, 31, v0
	v_lshrrev_b32_e32 v1, 27, v1
	v_add_u32_e32 v1, v0, v1
	v_ashrrev_i32_e32 v4, 5, v1
	v_and_b32_e32 v1, 0xffffffe0, v1
	v_sub_u32_e32 v11, v0, v1
	v_mul_lo_u32 v0, v4, s73
	v_lshl_add_u32 v0, v11, 4, v0
	ds_read_b128 v[0:3], v0
	v_ashrrev_i32_e32 v5, 31, v4
	v_lshl_add_u64 v[4:5], v[4:5], 0, s[80:81]
	v_mad_u64_u32 v[8:9], s[4:5], v4, s33, v[6:7]
	v_lshlrev_b32_e32 v4, 3, v11
	v_mad_i32_i24 v9, v5, s33, v9
	v_ashrrev_i32_e32 v5, 31, v4
	v_lshl_add_u64 v[4:5], v[4:5], 1, v[8:9]
	s_waitcnt lgkmcnt(0)
	global_store_dwordx4 v[4:5], v[0:3], off
	s_nop 1
	v_add_u32_e32 v0, 0x300, v10
	v_ashrrev_i32_e32 v1, 31, v0
	v_lshrrev_b32_e32 v1, 27, v1
	v_add_u32_e32 v1, v0, v1
	v_ashrrev_i32_e32 v4, 5, v1
	v_and_b32_e32 v1, 0xffffffe0, v1
	v_sub_u32_e32 v8, v0, v1
	v_mul_lo_u32 v0, v4, s73
	v_lshl_add_u32 v0, v8, 4, v0
	ds_read_b128 v[0:3], v0
	v_ashrrev_i32_e32 v5, 31, v4
	v_lshl_add_u64 v[4:5], v[4:5], 0, s[80:81]
	v_mad_u64_u32 v[6:7], s[4:5], v4, s33, v[6:7]
	v_lshlrev_b32_e32 v4, 3, v8
	v_mad_i32_i24 v7, v5, s33, v7
	v_ashrrev_i32_e32 v5, 31, v4
	v_lshl_add_u64 v[4:5], v[4:5], 1, v[6:7]
	s_waitcnt lgkmcnt(0)
	global_store_dwordx4 v[4:5], v[0:3], off
	s_cbranch_scc1 .LBB0_220
	s_cmp_eq_u32 s98, 2
	s_cbranch_scc1 .Lb_tile_late_done
.Lb_items:
	s_cmp_gt_i32 s36, 63
	s_mov_b64 s[0:1], -1
	s_cbranch_scc0 .LBB0_285
	s_cmpk_lt_u32 s36, 0x100
	s_cbranch_scc1 .LBB0_225
	s_and_b32 s14, s36, 0x7fffff80
	s_mov_b64 s[0:1], 0
	s_add_u32 s12, s90, s0
	s_addc_u32 s13, s91, s1
	s_addk_i32 s14, 0xb00
	s_add_i32 s0, s14, s28
	s_mov_b32 s1, s81
	s_lshl_b64 s[0:1], s[0:1], 11
	s_add_u32 s4, s12, s0
	s_addc_u32 s5, s13, s1
	s_add_u32 s10, s12, s26
	s_addc_u32 s11, s13, 0
	v_mov_b32_e32 v86, v176
	s_add_u32 s0, s4, 0x10000
	v_lshlrev_b32_e32 v0, 3, v86
	v_and_b32_e32 v0, 56, v0
	v_lshlrev_b32_e32 v1, 7, v86
	s_addc_u32 s1, s5, 0
	v_and_or_b32 v178, v1, s70, v0
	s_add_u32 s2, s4, 0x20000
	v_lshlrev_b64 v[28:29], 1, v[178:179]
	s_addc_u32 s3, s5, 0
	v_lshl_add_u64 v[72:73], s[4:5], 0, v[28:29]
	v_lshl_add_u64 v[4:5], s[0:1], 0, v[28:29]
	v_lshl_add_u64 v[8:9], s[2:3], 0, v[28:29]
	global_load_dwordx4 v[0:3], v[72:73], off
	s_nop 0
	global_load_dwordx4 v[4:7], v[4:5], off
	s_nop 0
	global_load_dwordx4 v[8:11], v[8:9], off
	s_add_u32 s4, s4, 0x30000
	s_addc_u32 s5, s5, 0
	s_add_u32 s6, s10, 0x2a50000
	s_addc_u32 s7, s11, 0
	s_add_u32 s8, s10, 0x2a60000
	s_addc_u32 s9, s11, 0
	v_lshl_add_u64 v[32:33], s[10:11], 0, v[28:29]
	s_add_u32 s10, s10, 0x2a70000
	v_add_co_u32_e32 v16, vcc, s74, v32
	s_addc_u32 s11, s11, 0
	v_lshl_add_u64 v[12:13], s[4:5], 0, v[28:29]
	v_addc_co_u32_e32 v17, vcc, 0, v33, vcc
	v_lshl_add_u64 v[20:21], s[6:7], 0, v[28:29]
	v_lshl_add_u64 v[24:25], s[8:9], 0, v[28:29]
	v_lshl_add_u64 v[28:29], s[10:11], 0, v[28:29]
	global_load_dwordx4 v[12:15], v[12:13], off
	v_ashrrev_i32_e32 v34, 1, v86
	global_load_dwordx4 v[16:19], v[16:17], off
	v_lshrrev_b32_e32 v36, 1, v86
	global_load_dwordx4 v[20:23], v[20:21], off
	v_lshlrev_b32_e32 v37, 4, v86
	global_load_dwordx4 v[24:27], v[24:25], off
	v_add_u32_e32 v39, 0x100, v86
	global_load_dwordx4 v[28:31], v[28:29], off
	v_add_u32_e32 v40, 0x200, v86
	v_and_b32_e32 v88, 0xffffffc0, v34
	v_lshrrev_b32_e32 v87, 3, v86
	v_and_b32_e32 v36, 16, v36
	v_and_b32_e32 v38, 0x70, v37
	v_lshrrev_b32_e32 v34, 3, v39
	v_lshrrev_b32_e32 v37, 3, v40
	v_and_or_b32 v39, v86, 31, v88
	v_mov_b32_e32 v35, v179
	v_mad_u64_u32 v[66:67], s[16:17], v87, s71, v[38:39]
	v_mad_u64_u32 v[68:69], s[16:17], v34, s71, v[38:39]
	v_mad_u64_u32 v[70:71], s[16:17], v37, s71, v[38:39]
	v_mad_u64_u32 v[64:65], s[16:17], v39, s71, v[36:37]
	v_or_b32_e32 v34, 64, v178
	v_lshlrev_b64 v[34:35], 1, v[34:35]
	s_mov_b64 s[16:17], 0x2a40000
	v_lshl_add_u64 v[84:85], v[32:33], 0, s[16:17]
	v_lshl_add_u64 v[32:33], s[0:1], 0, v[34:35]
	global_load_dwordx4 v[90:93], v[72:73], off offset:128
	v_lshl_add_u64 v[40:41], s[2:3], 0, v[34:35]
	global_load_dwordx4 v[94:97], v[32:33], off
	global_load_dwordx4 v[98:101], v[40:41], off
	v_lshl_add_u64 v[32:33], s[4:5], 0, v[34:35]
	global_load_dwordx4 v[102:105], v[84:85], off offset:128
	v_lshl_add_u64 v[40:41], s[6:7], 0, v[34:35]
	global_load_dwordx4 v[106:109], v[32:33], off
	global_load_dwordx4 v[110:113], v[40:41], off
	v_lshl_add_u64 v[32:33], s[8:9], 0, v[34:35]
	v_lshl_add_u64 v[34:35], s[10:11], 0, v[34:35]
	global_load_dwordx4 v[114:117], v[32:33], off
	global_load_dwordx4 v[118:121], v[34:35], off
	s_barrier
; #define GLOAD(dst, kt_) _Pragma("unroll") for (int i = 0; i < NCH; ++i) { dst[i] = (i < NCHW) ? ldw(i, tid >> 3, (kt_) * 64 + (tid & 7) * 8) : ldx(i - NCHW, tid >> 3, (kt_) * 64 + (tid & 7) * 8); }
; #define LSTORE(src, base) _Pragma("unroll") for (int i = 0; i < NCH; ++i) { const int c = tid + 256 * i; *(u32x4*)((base) + (c >> 3) * 144 + (c & 7) * 16) = src[i]; }
; template <int WGN, int INS, int IMS, bool DB, class LdW, class LdX>
; DI void gemm_core(f32x16 (&acc)[INS][IMS], const int KT, LdW ldw, LdX ldx, char* lds, const int tid) {
;     ...
;   if (DB) {
;     u32x4 preA[NCH], preB[NCH];
;     GLOAD(preA, 0)
;     GLOAD(preB, 1)
;     __syncthreads();
;     LSTORE(preA, lds)
;     __syncthreads();
;     for (int kt = 0; kt < KT; kt += 2) {
;       if (kt + 2 < KT) { GLOAD(preA, kt + 2) }
;       COMPUTE_PIPE(lds)
;       LSTORE(preB, lds + BUFB)
;       __syncthreads();
;       if (kt + 3 < KT) { GLOAD(preB, kt + 3) }
;       COMPUTE_PIPE(lds + BUFB)
;       if (kt + 2 < KT) { LSTORE(preA, lds) }
;       __syncthreads();
;     }
	v_and_b32_e32 v65, 0x5f, v86
	v_mad_u32_u24 v67, v65, s71, v36
	s_waitcnt vmcnt(15)
	ds_write_b128 v66, v[0:3]
	s_waitcnt vmcnt(14)
	ds_write_b128 v68, v[4:7]
	s_waitcnt vmcnt(13)
	ds_write_b128 v70, v[8:11]
	v_add_u32_e32 v0, 0x300, v86
	v_lshrrev_b32_e32 v0, 3, v0
	v_mad_u64_u32 v[74:75], s[16:17], v0, s71, v[38:39]
	v_add_u32_e32 v0, 0x400, v86
	v_lshrrev_b32_e32 v0, 3, v0
	v_mad_u64_u32 v[76:77], s[16:17], v0, s71, v[38:39]
	v_add_u32_e32 v0, 0x500, v86
	v_lshrrev_b32_e32 v0, 3, v0
	v_mad_u64_u32 v[78:79], s[16:17], v0, s71, v[38:39]
	v_add_u32_e32 v0, 0x600, v86
	v_lshrrev_b32_e32 v0, 3, v0
	v_mad_u64_u32 v[80:81], s[16:17], v0, s71, v[38:39]
	v_add_u32_e32 v0, 0x700, v86
	v_lshrrev_b32_e32 v0, 3, v0
	v_mad_u64_u32 v[82:83], s[16:17], v0, s71, v[38:39]
	s_waitcnt vmcnt(12)
	ds_write_b128 v74, v[12:15]
	s_waitcnt vmcnt(11)
	ds_write_b128 v76, v[16:19]
	s_waitcnt vmcnt(10)
	ds_write_b128 v78, v[20:23]
	s_waitcnt vmcnt(9)
	ds_write_b128 v80, v[24:27]
	s_waitcnt vmcnt(8)
	ds_write_b128 v82, v[28:31]
	s_waitcnt lgkmcnt(0)
	s_barrier
	ds_read_b128 v[0:3], v64
	ds_read_b128 v[4:7], v67 offset:18432
	ds_read_b128 v[122:125], v64 offset:32
	ds_read_b128 v[126:129], v67 offset:18464
	ds_read_b128 v[8:11], v64 offset:4608
	ds_read_b128 v[130:133], v64 offset:4640
	s_waitcnt lgkmcnt(4)
	v_mfma_f32_32x32x16_bf16 v[48:63], v[0:3], v[4:7], 0
	s_waitcnt lgkmcnt(1)
	v_mfma_f32_32x32x16_bf16 v[32:47], v[8:11], v[4:7], 0
	ds_read_b128 v[4:7], v67 offset:23040
	ds_read_b128 v[134:137], v67 offset:23072
	s_waitcnt lgkmcnt(1)
	v_mfma_f32_32x32x16_bf16 v[16:31], v[0:3], v[4:7], 0
	v_mfma_f32_32x32x16_bf16 v[0:15], v[8:11], v[4:7], 0
	v_mfma_f32_32x32x16_bf16 v[48:63], v[122:125], v[126:129], v[48:63]
	v_mfma_f32_32x32x16_bf16 v[32:47], v[130:133], v[126:129], v[32:47]
	s_waitcnt lgkmcnt(0)
	v_mfma_f32_32x32x16_bf16 v[16:31], v[122:125], v[134:137], v[16:31]
	v_mfma_f32_32x32x16_bf16 v[0:15], v[130:133], v[134:137], v[0:15]
	ds_read_b128 v[122:125], v64 offset:64
	ds_read_b128 v[126:129], v67 offset:18496
	ds_read_b128 v[130:133], v64 offset:96
	ds_read_b128 v[134:137], v67 offset:18528
	ds_read_b128 v[138:141], v64 offset:4672
	ds_read_b128 v[142:145], v64 offset:4704
	s_waitcnt lgkmcnt(4)
	v_mfma_f32_32x32x16_bf16 v[48:63], v[122:125], v[126:129], v[48:63]
	s_waitcnt lgkmcnt(1)
	v_mfma_f32_32x32x16_bf16 v[32:47], v[138:141], v[126:129], v[32:47]
	ds_read_b128 v[126:129], v67 offset:23104
	ds_read_b128 v[146:149], v67 offset:23136
	s_waitcnt lgkmcnt(1)
	v_mfma_f32_32x32x16_bf16 v[16:31], v[122:125], v[126:129], v[16:31]
	v_or_b32_e32 v122, 0x80, v178
	v_mov_b32_e32 v123, v179
	v_lshlrev_b64 v[154:155], 1, v[122:123]
	v_lshl_add_u64 v[122:123], s[0:1], 0, v[154:155]
	v_lshl_add_u64 v[150:151], s[4:5], 0, v[154:155]
	v_lshl_add_u64 v[152:153], s[6:7], 0, v[154:155]
	v_lshl_add_u64 v[156:157], s[8:9], 0, v[154:155]
	v_mfma_f32_32x32x16_bf16 v[0:15], v[138:141], v[126:129], v[0:15]
	v_lshl_add_u64 v[126:127], s[2:3], 0, v[154:155]
	v_lshl_add_u64 v[158:159], s[10:11], 0, v[154:155]
	global_load_dwordx4 v[122:125], v[122:123], off
	s_nop 0
	global_load_dwordx4 v[126:129], v[126:127], off
	v_mfma_f32_32x32x16_bf16 v[48:63], v[130:133], v[134:137], v[48:63]
	v_mfma_f32_32x32x16_bf16 v[32:47], v[142:145], v[134:137], v[32:47]
	global_load_dwordx4 v[134:137], v[72:73], off offset:256
	global_load_dwordx4 v[138:141], v[84:85], off offset:256
	s_waitcnt lgkmcnt(0)
	v_mfma_f32_32x32x16_bf16 v[16:31], v[130:133], v[146:149], v[16:31]
	global_load_dwordx4 v[130:133], v[150:151], off
	s_nop 0
	global_load_dwordx4 v[150:153], v[152:153], off
	s_nop 0
	global_load_dwordx4 v[154:157], v[156:157], off
	s_nop 0
	global_load_dwordx4 v[158:161], v[158:159], off
	s_waitcnt vmcnt(15)
	ds_write_b128 v66, v[90:93] offset:36864
	s_waitcnt vmcnt(14)
	ds_write_b128 v68, v[94:97] offset:36864
	s_waitcnt vmcnt(13)
	ds_write_b128 v70, v[98:101] offset:36864
	s_waitcnt vmcnt(11)
	ds_write_b128 v74, v[106:109] offset:36864
	ds_write_b128 v76, v[102:105] offset:36864
	s_waitcnt vmcnt(10)
	ds_write_b128 v78, v[110:113] offset:36864
	s_waitcnt vmcnt(9)
	ds_write_b128 v80, v[114:117] offset:36864
	s_waitcnt vmcnt(8)
	ds_write_b128 v82, v[118:121] offset:36864
	s_waitcnt lgkmcnt(0)
	s_barrier
	ds_read_b128 v[90:93], v64 offset:36864
	ds_read_b128 v[94:97], v67 offset:55296
	ds_read_b128 v[98:101], v64 offset:36896
	ds_read_b128 v[102:105], v67 offset:55328
	v_mfma_f32_32x32x16_bf16 v[0:15], v[142:145], v[146:149], v[0:15]
	ds_read_b128 v[106:109], v64 offset:41472
	ds_read_b128 v[110:113], v64 offset:41504
	s_waitcnt lgkmcnt(4)
	v_mfma_f32_32x32x16_bf16 v[48:63], v[90:93], v[94:97], v[48:63]
	s_waitcnt lgkmcnt(1)
	v_mfma_f32_32x32x16_bf16 v[32:47], v[106:109], v[94:97], v[32:47]
	ds_read_b128 v[94:97], v67 offset:59904
	ds_read_b128 v[114:117], v67 offset:59936
	s_waitcnt lgkmcnt(1)
	v_mfma_f32_32x32x16_bf16 v[16:31], v[90:93], v[94:97], v[16:31]
	v_mfma_f32_32x32x16_bf16 v[0:15], v[106:109], v[94:97], v[0:15]
	v_mfma_f32_32x32x16_bf16 v[48:63], v[98:101], v[102:105], v[48:63]
	v_mfma_f32_32x32x16_bf16 v[32:47], v[110:113], v[102:105], v[32:47]
	s_waitcnt lgkmcnt(0)
	v_mfma_f32_32x32x16_bf16 v[16:31], v[98:101], v[114:117], v[16:31]
	ds_read_b128 v[90:93], v64 offset:36928
	ds_read_b128 v[94:97], v67 offset:55360
	ds_read_b128 v[98:101], v64 offset:36960
	ds_read_b128 v[102:105], v67 offset:55392
	v_mfma_f32_32x32x16_bf16 v[0:15], v[110:113], v[114:117], v[0:15]
	ds_read_b128 v[106:109], v64 offset:41536
	ds_read_b128 v[110:113], v64 offset:41568
	s_waitcnt lgkmcnt(4)
	v_mfma_f32_32x32x16_bf16 v[48:63], v[90:93], v[94:97], v[48:63]
	s_waitcnt lgkmcnt(1)
; #define GLOAD(dst, kt_) _Pragma("unroll") for (int i = 0; i < NCH; ++i) { dst[i] = (i < NCHW) ? ldw(i, tid >> 3, (kt_) * 64 + (tid & 7) * 8) : ldx(i - NCHW, tid >> 3, (kt_) * 64 + (tid & 7) * 8); }
; #define LSTORE(src, base) _Pragma("unroll") for (int i = 0; i < NCH; ++i) { const int c = tid + 256 * i; *(u32x4*)((base) + (c >> 3) * 144 + (c & 7) * 16) = src[i]; }
; template <int WGN, int INS, int IMS, bool DB, class LdW, class LdX>
; DI void gemm_core(f32x16 (&acc)[INS][IMS], const int KT, LdW ldw, LdX ldx, char* lds, const int tid) {
;     ...
;   if (DB) {
;     u32x4 preA[NCH], preB[NCH];
;     GLOAD(preA, 0)
;     GLOAD(preB, 1)
;     __syncthreads();
;     LSTORE(preA, lds)
;     __syncthreads();
;     for (int kt = 0; kt < KT; kt += 2) {
;       if (kt + 2 < KT) { GLOAD(preA, kt + 2) }
;       COMPUTE_PIPE(lds)
;       LSTORE(preB, lds + BUFB)
;       __syncthreads();
;       if (kt + 3 < KT) { GLOAD(preB, kt + 3) }
;       COMPUTE_PIPE(lds + BUFB)
;       if (kt + 2 < KT) { LSTORE(preA, lds) }
;       __syncthreads();
;     }
	v_mfma_f32_32x32x16_bf16 v[32:47], v[106:109], v[94:97], v[32:47]
	ds_read_b128 v[94:97], v67 offset:59968
	ds_read_b128 v[114:117], v67 offset:60000
	s_waitcnt lgkmcnt(1)
	v_mfma_f32_32x32x16_bf16 v[16:31], v[90:93], v[94:97], v[16:31]
	v_or_b32_e32 v90, 0xc0, v178
	v_mov_b32_e32 v91, v179
	v_lshlrev_b64 v[142:143], 1, v[90:91]
	v_lshl_add_u64 v[90:91], s[0:1], 0, v[142:143]
	v_lshl_add_u64 v[118:119], s[4:5], 0, v[142:143]
	v_lshl_add_u64 v[120:121], s[6:7], 0, v[142:143]
	v_lshl_add_u64 v[144:145], s[8:9], 0, v[142:143]
	v_mfma_f32_32x32x16_bf16 v[0:15], v[106:109], v[94:97], v[0:15]
	v_lshl_add_u64 v[94:95], s[2:3], 0, v[142:143]
	v_lshl_add_u64 v[146:147], s[10:11], 0, v[142:143]
	global_load_dwordx4 v[90:93], v[90:91], off
	s_nop 0
	global_load_dwordx4 v[94:97], v[94:95], off
	v_mfma_f32_32x32x16_bf16 v[48:63], v[98:101], v[102:105], v[48:63]
	v_mfma_f32_32x32x16_bf16 v[32:47], v[110:113], v[102:105], v[32:47]
	global_load_dwordx4 v[102:105], v[72:73], off offset:384
	global_load_dwordx4 v[106:109], v[84:85], off offset:384
	s_waitcnt lgkmcnt(0)
	v_mfma_f32_32x32x16_bf16 v[16:31], v[98:101], v[114:117], v[16:31]
	global_load_dwordx4 v[98:101], v[118:119], off
	s_nop 0
	global_load_dwordx4 v[118:121], v[120:121], off
	s_nop 0
	global_load_dwordx4 v[142:145], v[144:145], off
	s_nop 0
	global_load_dwordx4 v[146:149], v[146:147], off
	s_waitcnt vmcnt(13)
	ds_write_b128 v66, v[134:137]
	ds_write_b128 v68, v[122:125]
	ds_write_b128 v70, v[126:129]
	s_waitcnt vmcnt(11)
	ds_write_b128 v74, v[130:133]
	ds_write_b128 v76, v[138:141]
	s_waitcnt vmcnt(10)
	ds_write_b128 v78, v[150:153]
	s_waitcnt vmcnt(9)
	ds_write_b128 v80, v[154:157]
	s_waitcnt vmcnt(8)
	ds_write_b128 v82, v[158:161]
	s_waitcnt lgkmcnt(0)
	s_barrier
	v_mfma_f32_32x32x16_bf16 v[0:15], v[110:113], v[114:117], v[0:15]
	ds_read_b128 v[110:113], v64
	ds_read_b128 v[114:117], v67 offset:18432
	ds_read_b128 v[122:125], v64 offset:32
	ds_read_b128 v[126:129], v67 offset:18464
	ds_read_b128 v[130:133], v64 offset:4608
	ds_read_b128 v[134:137], v64 offset:4640
	s_waitcnt lgkmcnt(4)
	v_mfma_f32_32x32x16_bf16 v[48:63], v[110:113], v[114:117], v[48:63]
	s_waitcnt lgkmcnt(1)
	v_mfma_f32_32x32x16_bf16 v[32:47], v[130:133], v[114:117], v[32:47]
	ds_read_b128 v[114:117], v67 offset:23040
	ds_read_b128 v[138:141], v67 offset:23072
	s_waitcnt lgkmcnt(1)
	v_mfma_f32_32x32x16_bf16 v[16:31], v[110:113], v[114:117], v[16:31]
	v_mfma_f32_32x32x16_bf16 v[0:15], v[130:133], v[114:117], v[0:15]
	v_mfma_f32_32x32x16_bf16 v[48:63], v[122:125], v[126:129], v[48:63]
	v_mfma_f32_32x32x16_bf16 v[32:47], v[134:137], v[126:129], v[32:47]
	s_waitcnt lgkmcnt(0)
	v_mfma_f32_32x32x16_bf16 v[16:31], v[122:125], v[138:141], v[16:31]
	ds_read_b128 v[110:113], v64 offset:64
	ds_read_b128 v[114:117], v67 offset:18496
	ds_read_b128 v[122:125], v64 offset:96
	ds_read_b128 v[126:129], v67 offset:18528
	v_mfma_f32_32x32x16_bf16 v[0:15], v[134:137], v[138:141], v[0:15]
	ds_read_b128 v[130:133], v64 offset:4672
	ds_read_b128 v[134:137], v64 offset:4704
	s_waitcnt lgkmcnt(4)
	v_mfma_f32_32x32x16_bf16 v[48:63], v[110:113], v[114:117], v[48:63]
	s_waitcnt lgkmcnt(1)
	v_mfma_f32_32x32x16_bf16 v[32:47], v[130:133], v[114:117], v[32:47]
	ds_read_b128 v[114:117], v67 offset:23104
	ds_read_b128 v[138:141], v67 offset:23136
	s_waitcnt lgkmcnt(1)
	v_mfma_f32_32x32x16_bf16 v[16:31], v[110:113], v[114:117], v[16:31]
	v_or_b32_e32 v110, 0x100, v178
	v_mov_b32_e32 v111, v179
	v_lshlrev_b64 v[154:155], 1, v[110:111]
	v_lshl_add_u64 v[110:111], s[0:1], 0, v[154:155]
	v_lshl_add_u64 v[150:151], s[4:5], 0, v[154:155]
	v_lshl_add_u64 v[152:153], s[6:7], 0, v[154:155]
	v_lshl_add_u64 v[156:157], s[8:9], 0, v[154:155]
	v_mfma_f32_32x32x16_bf16 v[0:15], v[130:133], v[114:117], v[0:15]
	v_lshl_add_u64 v[114:115], s[2:3], 0, v[154:155]
	v_lshl_add_u64 v[158:159], s[10:11], 0, v[154:155]
	global_load_dwordx4 v[110:113], v[110:111], off
	s_nop 0
	global_load_dwordx4 v[114:117], v[114:115], off
	v_mfma_f32_32x32x16_bf16 v[48:63], v[122:125], v[126:129], v[48:63]
	v_mfma_f32_32x32x16_bf16 v[32:47], v[134:137], v[126:129], v[32:47]
	global_load_dwordx4 v[126:129], v[72:73], off offset:512
	global_load_dwordx4 v[130:133], v[84:85], off offset:512
	s_waitcnt lgkmcnt(0)
	v_mfma_f32_32x32x16_bf16 v[16:31], v[122:125], v[138:141], v[16:31]
	global_load_dwordx4 v[122:125], v[150:151], off
	s_nop 0
	global_load_dwordx4 v[150:153], v[152:153], off
	s_nop 0
	global_load_dwordx4 v[154:157], v[156:157], off
	s_nop 0
	global_load_dwordx4 v[158:161], v[158:159], off
	s_waitcnt vmcnt(13)
	ds_write_b128 v66, v[102:105] offset:36864
	ds_write_b128 v68, v[90:93] offset:36864
	ds_write_b128 v70, v[94:97] offset:36864
	s_waitcnt vmcnt(11)
	ds_write_b128 v74, v[98:101] offset:36864
	ds_write_b128 v76, v[106:109] offset:36864
	s_waitcnt vmcnt(10)
	ds_write_b128 v78, v[118:121] offset:36864
	s_waitcnt vmcnt(9)
	ds_write_b128 v80, v[142:145] offset:36864
	s_waitcnt vmcnt(8)
	ds_write_b128 v82, v[146:149] offset:36864
	s_waitcnt lgkmcnt(0)
	s_barrier
; #define GLOAD(dst, kt_) _Pragma("unroll") for (int i = 0; i < NCH; ++i) { dst[i] = (i < NCHW) ? ldw(i, tid >> 3, (kt_) * 64 + (tid & 7) * 8) : ldx(i - NCHW, tid >> 3, (kt_) * 64 + (tid & 7) * 8); }
; #define LSTORE(src, base) _Pragma("unroll") for (int i = 0; i < NCH; ++i) { const int c = tid + 256 * i; *(u32x4*)((base) + (c >> 3) * 144 + (c & 7) * 16) = src[i]; }
; template <int WGN, int INS, int IMS, bool DB, class LdW, class LdX>
; DI void gemm_core(f32x16 (&acc)[INS][IMS], const int KT, LdW ldw, LdX ldx, char* lds, const int tid) {
;     ...
;   if (DB) {
;     u32x4 preA[NCH], preB[NCH];
;     GLOAD(preA, 0)
;     GLOAD(preB, 1)
;     __syncthreads();
;     LSTORE(preA, lds)
;     __syncthreads();
;     for (int kt = 0; kt < KT; kt += 2) {
;       if (kt + 2 < KT) { GLOAD(preA, kt + 2) }
;       COMPUTE_PIPE(lds)
;       LSTORE(preB, lds + BUFB)
;       __syncthreads();
;       if (kt + 3 < KT) { GLOAD(preB, kt + 3) }
;       COMPUTE_PIPE(lds + BUFB)
;       if (kt + 2 < KT) { LSTORE(preA, lds) }
;       __syncthreads();
;     }
	ds_read_b128 v[90:93], v64 offset:36864
	ds_read_b128 v[94:97], v67 offset:55296
	ds_read_b128 v[98:101], v64 offset:36896
	ds_read_b128 v[102:105], v67 offset:55328
	v_mfma_f32_32x32x16_bf16 v[0:15], v[134:137], v[138:141], v[0:15]
	ds_read_b128 v[106:109], v64 offset:41472
	ds_read_b128 v[118:121], v64 offset:41504
	s_waitcnt lgkmcnt(4)
	v_mfma_f32_32x32x16_bf16 v[48:63], v[90:93], v[94:97], v[48:63]
	s_waitcnt lgkmcnt(1)
	v_mfma_f32_32x32x16_bf16 v[32:47], v[106:109], v[94:97], v[32:47]
	ds_read_b128 v[94:97], v67 offset:59904
	ds_read_b128 v[134:137], v67 offset:59936
	s_waitcnt lgkmcnt(1)
	v_mfma_f32_32x32x16_bf16 v[16:31], v[90:93], v[94:97], v[16:31]
	v_mfma_f32_32x32x16_bf16 v[0:15], v[106:109], v[94:97], v[0:15]
	v_mfma_f32_32x32x16_bf16 v[48:63], v[98:101], v[102:105], v[48:63]
	v_mfma_f32_32x32x16_bf16 v[32:47], v[118:121], v[102:105], v[32:47]
	s_waitcnt lgkmcnt(0)
	v_mfma_f32_32x32x16_bf16 v[16:31], v[98:101], v[134:137], v[16:31]
	ds_read_b128 v[90:93], v64 offset:36928
	ds_read_b128 v[94:97], v67 offset:55360
	ds_read_b128 v[98:101], v64 offset:36960
	ds_read_b128 v[102:105], v67 offset:55392
	v_mfma_f32_32x32x16_bf16 v[0:15], v[118:121], v[134:137], v[0:15]
	ds_read_b128 v[106:109], v64 offset:41536
	ds_read_b128 v[118:121], v64 offset:41568
	s_waitcnt lgkmcnt(4)
	v_mfma_f32_32x32x16_bf16 v[48:63], v[90:93], v[94:97], v[48:63]
	s_waitcnt lgkmcnt(1)
	v_mfma_f32_32x32x16_bf16 v[32:47], v[106:109], v[94:97], v[32:47]
	ds_read_b128 v[94:97], v67 offset:59968
	ds_read_b128 v[134:137], v67 offset:60000
	s_waitcnt lgkmcnt(1)
	v_mfma_f32_32x32x16_bf16 v[16:31], v[90:93], v[94:97], v[16:31]
	v_or_b32_e32 v90, 0x140, v178
	v_mov_b32_e32 v91, v179
	v_lshlrev_b64 v[142:143], 1, v[90:91]
	v_lshl_add_u64 v[90:91], s[0:1], 0, v[142:143]
	v_lshl_add_u64 v[138:139], s[4:5], 0, v[142:143]
	v_lshl_add_u64 v[140:141], s[6:7], 0, v[142:143]
	v_lshl_add_u64 v[144:145], s[8:9], 0, v[142:143]
	v_mfma_f32_32x32x16_bf16 v[0:15], v[106:109], v[94:97], v[0:15]
	v_lshl_add_u64 v[94:95], s[2:3], 0, v[142:143]
	v_lshl_add_u64 v[146:147], s[10:11], 0, v[142:143]
	global_load_dwordx4 v[90:93], v[90:91], off
	s_nop 0
	global_load_dwordx4 v[94:97], v[94:95], off
	v_mfma_f32_32x32x16_bf16 v[48:63], v[98:101], v[102:105], v[48:63]
	v_mfma_f32_32x32x16_bf16 v[32:47], v[118:121], v[102:105], v[32:47]
	global_load_dwordx4 v[102:105], v[72:73], off offset:640
	global_load_dwordx4 v[106:109], v[84:85], off offset:640
	s_waitcnt lgkmcnt(0)
	v_mfma_f32_32x32x16_bf16 v[16:31], v[98:101], v[134:137], v[16:31]
	global_load_dwordx4 v[98:101], v[138:139], off
	s_nop 0
	global_load_dwordx4 v[138:141], v[140:141], off
	s_nop 0
	global_load_dwordx4 v[142:145], v[144:145], off
	s_nop 0
	global_load_dwordx4 v[146:149], v[146:147], off
	s_waitcnt vmcnt(13)
	ds_write_b128 v66, v[126:129]
	ds_write_b128 v68, v[110:113]
	ds_write_b128 v70, v[114:117]
	s_waitcnt vmcnt(11)
	ds_write_b128 v74, v[122:125]
	ds_write_b128 v76, v[130:133]
	s_waitcnt vmcnt(10)
	ds_write_b128 v78, v[150:153]
	s_waitcnt vmcnt(9)
	ds_write_b128 v80, v[154:157]
	s_waitcnt vmcnt(8)
	ds_write_b128 v82, v[158:161]
	s_waitcnt lgkmcnt(0)
	s_barrier
	v_mfma_f32_32x32x16_bf16 v[0:15], v[118:121], v[134:137], v[0:15]
	ds_read_b128 v[110:113], v64
	ds_read_b128 v[114:117], v67 offset:18432
	ds_read_b128 v[118:121], v64 offset:32
	ds_read_b128 v[122:125], v67 offset:18464
	ds_read_b128 v[126:129], v64 offset:4608
	ds_read_b128 v[130:133], v64 offset:4640
	s_waitcnt lgkmcnt(4)
	v_mfma_f32_32x32x16_bf16 v[48:63], v[110:113], v[114:117], v[48:63]
	s_waitcnt lgkmcnt(1)
	v_mfma_f32_32x32x16_bf16 v[32:47], v[126:129], v[114:117], v[32:47]
	ds_read_b128 v[114:117], v67 offset:23040
	ds_read_b128 v[134:137], v67 offset:23072
	s_waitcnt lgkmcnt(1)
	v_mfma_f32_32x32x16_bf16 v[16:31], v[110:113], v[114:117], v[16:31]
	v_mfma_f32_32x32x16_bf16 v[0:15], v[126:129], v[114:117], v[0:15]
	v_mfma_f32_32x32x16_bf16 v[48:63], v[118:121], v[122:125], v[48:63]
	v_mfma_f32_32x32x16_bf16 v[32:47], v[130:133], v[122:125], v[32:47]
	s_waitcnt lgkmcnt(0)
	v_mfma_f32_32x32x16_bf16 v[16:31], v[118:121], v[134:137], v[16:31]
	ds_read_b128 v[110:113], v64 offset:64
	ds_read_b128 v[114:117], v67 offset:18496
	ds_read_b128 v[118:121], v64 offset:96
	ds_read_b128 v[122:125], v67 offset:18528
	v_mfma_f32_32x32x16_bf16 v[0:15], v[130:133], v[134:137], v[0:15]
	ds_read_b128 v[126:129], v64 offset:4672
	ds_read_b128 v[130:133], v64 offset:4704
	s_waitcnt lgkmcnt(4)
	v_mfma_f32_32x32x16_bf16 v[48:63], v[110:113], v[114:117], v[48:63]
	s_waitcnt lgkmcnt(1)
	v_mfma_f32_32x32x16_bf16 v[32:47], v[126:129], v[114:117], v[32:47]
	ds_read_b128 v[114:117], v67 offset:23104
	ds_read_b128 v[134:137], v67 offset:23136
	s_waitcnt lgkmcnt(1)
	v_mfma_f32_32x32x16_bf16 v[16:31], v[110:113], v[114:117], v[16:31]
	v_or_b32_e32 v110, 0x180, v178
	v_mov_b32_e32 v111, v179
	v_lshlrev_b64 v[154:155], 1, v[110:111]
	v_lshl_add_u64 v[110:111], s[0:1], 0, v[154:155]
	v_lshl_add_u64 v[150:151], s[4:5], 0, v[154:155]
	v_lshl_add_u64 v[152:153], s[6:7], 0, v[154:155]
	v_lshl_add_u64 v[156:157], s[8:9], 0, v[154:155]
	v_mfma_f32_32x32x16_bf16 v[0:15], v[126:129], v[114:117], v[0:15]
	v_lshl_add_u64 v[114:115], s[2:3], 0, v[154:155]
	v_lshl_add_u64 v[158:159], s[10:11], 0, v[154:155]
	global_load_dwordx4 v[110:113], v[110:111], off
	s_nop 0
	global_load_dwordx4 v[114:117], v[114:115], off
	v_mfma_f32_32x32x16_bf16 v[48:63], v[118:121], v[122:125], v[48:63]
	v_mfma_f32_32x32x16_bf16 v[32:47], v[130:133], v[122:125], v[32:47]
	global_load_dwordx4 v[122:125], v[72:73], off offset:768
	global_load_dwordx4 v[126:129], v[84:85], off offset:768
	s_waitcnt lgkmcnt(0)
	v_mfma_f32_32x32x16_bf16 v[16:31], v[118:121], v[134:137], v[16:31]
	global_load_dwordx4 v[118:121], v[150:151], off
	s_nop 0
	global_load_dwordx4 v[150:153], v[152:153], off
	s_nop 0
	global_load_dwordx4 v[154:157], v[156:157], off
	s_nop 0
	global_load_dwordx4 v[158:161], v[158:159], off
	s_waitcnt vmcnt(13)
	ds_write_b128 v66, v[102:105] offset:36864
	ds_write_b128 v68, v[90:93] offset:36864
	ds_write_b128 v70, v[94:97] offset:36864
	s_waitcnt vmcnt(11)
	ds_write_b128 v74, v[98:101] offset:36864
	ds_write_b128 v76, v[106:109] offset:36864
	s_waitcnt vmcnt(10)
	ds_write_b128 v78, v[138:141] offset:36864
	s_waitcnt vmcnt(9)
	ds_write_b128 v80, v[142:145] offset:36864
	s_waitcnt vmcnt(8)
	ds_write_b128 v82, v[146:149] offset:36864
	s_waitcnt lgkmcnt(0)
	s_barrier
; #define GLOAD(dst, kt_) _Pragma("unroll") for (int i = 0; i < NCH; ++i) { dst[i] = (i < NCHW) ? ldw(i, tid >> 3, (kt_) * 64 + (tid & 7) * 8) : ldx(i - NCHW, tid >> 3, (kt_) * 64 + (tid & 7) * 8); }
; #define LSTORE(src, base) _Pragma("unroll") for (int i = 0; i < NCH; ++i) { const int c = tid + 256 * i; *(u32x4*)((base) + (c >> 3) * 144 + (c & 7) * 16) = src[i]; }
; template <int WGN, int INS, int IMS, bool DB, class LdW, class LdX>
; DI void gemm_core(f32x16 (&acc)[INS][IMS], const int KT, LdW ldw, LdX ldx, char* lds, const int tid) {
;     ...
;   if (DB) {
;     u32x4 preA[NCH], preB[NCH];
;     GLOAD(preA, 0)
;     GLOAD(preB, 1)
;     __syncthreads();
;     LSTORE(preA, lds)
;     __syncthreads();
;     for (int kt = 0; kt < KT; kt += 2) {
;       if (kt + 2 < KT) { GLOAD(preA, kt + 2) }
;       COMPUTE_PIPE(lds)
;       LSTORE(preB, lds + BUFB)
;       __syncthreads();
;       if (kt + 3 < KT) { GLOAD(preB, kt + 3) }
;       COMPUTE_PIPE(lds + BUFB)
;       if (kt + 2 < KT) { LSTORE(preA, lds) }
;       __syncthreads();
;     }
	ds_read_b128 v[90:93], v64 offset:36864
	ds_read_b128 v[94:97], v67 offset:55296
	ds_read_b128 v[98:101], v64 offset:36896
	ds_read_b128 v[102:105], v67 offset:55328
	v_mfma_f32_32x32x16_bf16 v[0:15], v[130:133], v[134:137], v[0:15]
	ds_read_b128 v[106:109], v64 offset:41472
	ds_read_b128 v[130:133], v64 offset:41504
	s_waitcnt lgkmcnt(4)
	v_mfma_f32_32x32x16_bf16 v[48:63], v[90:93], v[94:97], v[48:63]
	s_waitcnt lgkmcnt(1)
	v_mfma_f32_32x32x16_bf16 v[32:47], v[106:109], v[94:97], v[32:47]
	ds_read_b128 v[94:97], v67 offset:59904
	ds_read_b128 v[134:137], v67 offset:59936
	s_waitcnt lgkmcnt(1)
	v_mfma_f32_32x32x16_bf16 v[16:31], v[90:93], v[94:97], v[16:31]
	v_mfma_f32_32x32x16_bf16 v[0:15], v[106:109], v[94:97], v[0:15]
	v_mfma_f32_32x32x16_bf16 v[48:63], v[98:101], v[102:105], v[48:63]
	v_mfma_f32_32x32x16_bf16 v[32:47], v[130:133], v[102:105], v[32:47]
	s_waitcnt lgkmcnt(0)
	v_mfma_f32_32x32x16_bf16 v[16:31], v[98:101], v[134:137], v[16:31]
	ds_read_b128 v[90:93], v64 offset:36928
	ds_read_b128 v[94:97], v67 offset:55360
	ds_read_b128 v[98:101], v64 offset:36960
	ds_read_b128 v[102:105], v67 offset:55392
	v_mfma_f32_32x32x16_bf16 v[0:15], v[130:133], v[134:137], v[0:15]
	ds_read_b128 v[106:109], v64 offset:41536
	ds_read_b128 v[130:133], v64 offset:41568
	s_waitcnt lgkmcnt(4)
	v_mfma_f32_32x32x16_bf16 v[48:63], v[90:93], v[94:97], v[48:63]
	s_waitcnt lgkmcnt(1)
	v_mfma_f32_32x32x16_bf16 v[32:47], v[106:109], v[94:97], v[32:47]
	ds_read_b128 v[94:97], v67 offset:59968
	ds_read_b128 v[134:137], v67 offset:60000
	s_waitcnt lgkmcnt(1)
	v_mfma_f32_32x32x16_bf16 v[16:31], v[90:93], v[94:97], v[16:31]
	v_or_b32_e32 v90, 0x1c0, v178
	v_mov_b32_e32 v91, v179
	v_lshlrev_b64 v[142:143], 1, v[90:91]
	v_lshl_add_u64 v[90:91], s[0:1], 0, v[142:143]
	v_lshl_add_u64 v[138:139], s[4:5], 0, v[142:143]
	v_lshl_add_u64 v[140:141], s[6:7], 0, v[142:143]
	v_lshl_add_u64 v[144:145], s[8:9], 0, v[142:143]
	v_mfma_f32_32x32x16_bf16 v[0:15], v[106:109], v[94:97], v[0:15]
	v_lshl_add_u64 v[94:95], s[2:3], 0, v[142:143]
	v_lshl_add_u64 v[146:147], s[10:11], 0, v[142:143]
	global_load_dwordx4 v[90:93], v[90:91], off
	s_nop 0
	global_load_dwordx4 v[94:97], v[94:95], off
	v_mfma_f32_32x32x16_bf16 v[48:63], v[98:101], v[102:105], v[48:63]
	v_mfma_f32_32x32x16_bf16 v[32:47], v[130:133], v[102:105], v[32:47]
	global_load_dwordx4 v[102:105], v[72:73], off offset:896
	global_load_dwordx4 v[106:109], v[84:85], off offset:896
	s_waitcnt lgkmcnt(0)
	v_mfma_f32_32x32x16_bf16 v[16:31], v[98:101], v[134:137], v[16:31]
	global_load_dwordx4 v[98:101], v[138:139], off
	s_nop 0
	global_load_dwordx4 v[138:141], v[140:141], off
	s_nop 0
	global_load_dwordx4 v[142:145], v[144:145], off
	s_nop 0
	global_load_dwordx4 v[146:149], v[146:147], off
	s_waitcnt vmcnt(13)
	ds_write_b128 v66, v[122:125]
	ds_write_b128 v68, v[110:113]
	ds_write_b128 v70, v[114:117]
	s_waitcnt vmcnt(11)
	ds_write_b128 v74, v[118:121]
	ds_write_b128 v76, v[126:129]
	s_waitcnt vmcnt(10)
	ds_write_b128 v78, v[150:153]
	s_waitcnt vmcnt(9)
	ds_write_b128 v80, v[154:157]
	s_waitcnt vmcnt(8)
	ds_write_b128 v82, v[158:161]
	s_waitcnt lgkmcnt(0)
	s_barrier
	ds_read_b128 v[110:113], v64
	ds_read_b128 v[114:117], v67 offset:18432
	ds_read_b128 v[118:121], v64 offset:32
	ds_read_b128 v[122:125], v67 offset:18464
	v_mfma_f32_32x32x16_bf16 v[0:15], v[130:133], v[134:137], v[0:15]
	ds_read_b128 v[126:129], v64 offset:4608
	ds_read_b128 v[130:133], v64 offset:4640
	s_waitcnt lgkmcnt(4)
	v_mfma_f32_32x32x16_bf16 v[48:63], v[110:113], v[114:117], v[48:63]
	s_waitcnt lgkmcnt(1)
	v_mfma_f32_32x32x16_bf16 v[32:47], v[126:129], v[114:117], v[32:47]
	ds_read_b128 v[114:117], v67 offset:23040
	ds_read_b128 v[134:137], v67 offset:23072
	s_waitcnt lgkmcnt(1)
	v_mfma_f32_32x32x16_bf16 v[16:31], v[110:113], v[114:117], v[16:31]
	v_mfma_f32_32x32x16_bf16 v[0:15], v[126:129], v[114:117], v[0:15]
	v_mfma_f32_32x32x16_bf16 v[48:63], v[118:121], v[122:125], v[48:63]
	v_mfma_f32_32x32x16_bf16 v[32:47], v[130:133], v[122:125], v[32:47]
	s_waitcnt lgkmcnt(0)
	v_mfma_f32_32x32x16_bf16 v[16:31], v[118:121], v[134:137], v[16:31]
	ds_read_b128 v[110:113], v64 offset:64
	ds_read_b128 v[114:117], v67 offset:18496
	ds_read_b128 v[118:121], v64 offset:96
	ds_read_b128 v[122:125], v67 offset:18528
	v_mfma_f32_32x32x16_bf16 v[0:15], v[130:133], v[134:137], v[0:15]
	ds_read_b128 v[126:129], v64 offset:4672
	ds_read_b128 v[130:133], v64 offset:4704
	s_waitcnt lgkmcnt(4)
	v_mfma_f32_32x32x16_bf16 v[48:63], v[110:113], v[114:117], v[48:63]
	s_waitcnt lgkmcnt(1)
	v_mfma_f32_32x32x16_bf16 v[32:47], v[126:129], v[114:117], v[32:47]
	ds_read_b128 v[114:117], v67 offset:23104
	ds_read_b128 v[134:137], v67 offset:23136
	s_waitcnt lgkmcnt(1)
	v_mfma_f32_32x32x16_bf16 v[16:31], v[110:113], v[114:117], v[16:31]
	v_or_b32_e32 v110, 0x200, v178
	v_mov_b32_e32 v111, v179
	v_lshlrev_b64 v[154:155], 1, v[110:111]
	v_lshl_add_u64 v[110:111], s[0:1], 0, v[154:155]
	v_lshl_add_u64 v[150:151], s[4:5], 0, v[154:155]
	v_lshl_add_u64 v[152:153], s[6:7], 0, v[154:155]
	v_lshl_add_u64 v[156:157], s[8:9], 0, v[154:155]
	v_mfma_f32_32x32x16_bf16 v[0:15], v[126:129], v[114:117], v[0:15]
	v_lshl_add_u64 v[114:115], s[2:3], 0, v[154:155]
	v_lshl_add_u64 v[158:159], s[10:11], 0, v[154:155]
	global_load_dwordx4 v[110:113], v[110:111], off
	s_nop 0
	global_load_dwordx4 v[114:117], v[114:115], off
	v_mfma_f32_32x32x16_bf16 v[48:63], v[118:121], v[122:125], v[48:63]
	v_mfma_f32_32x32x16_bf16 v[32:47], v[130:133], v[122:125], v[32:47]
	global_load_dwordx4 v[122:125], v[72:73], off offset:1024
	global_load_dwordx4 v[126:129], v[84:85], off offset:1024
	s_waitcnt lgkmcnt(0)
	v_mfma_f32_32x32x16_bf16 v[16:31], v[118:121], v[134:137], v[16:31]
	global_load_dwordx4 v[118:121], v[150:151], off
	s_nop 0
	global_load_dwordx4 v[150:153], v[152:153], off
	s_nop 0
	global_load_dwordx4 v[154:157], v[156:157], off
	s_nop 0
	global_load_dwordx4 v[158:161], v[158:159], off
	s_waitcnt vmcnt(13)
	ds_write_b128 v66, v[102:105] offset:36864
	ds_write_b128 v68, v[90:93] offset:36864
	ds_write_b128 v70, v[94:97] offset:36864
	s_waitcnt vmcnt(11)
	ds_write_b128 v74, v[98:101] offset:36864
	ds_write_b128 v76, v[106:109] offset:36864
	s_waitcnt vmcnt(10)
	ds_write_b128 v78, v[138:141] offset:36864
	s_waitcnt vmcnt(9)
	ds_write_b128 v80, v[142:145] offset:36864
	s_waitcnt vmcnt(8)
	ds_write_b128 v82, v[146:149] offset:36864
	s_waitcnt lgkmcnt(0)
	s_barrier
; #define GLOAD(dst, kt_) _Pragma("unroll") for (int i = 0; i < NCH; ++i) { dst[i] = (i < NCHW) ? ldw(i, tid >> 3, (kt_) * 64 + (tid & 7) * 8) : ldx(i - NCHW, tid >> 3, (kt_) * 64 + (tid & 7) * 8); }
; #define LSTORE(src, base) _Pragma("unroll") for (int i = 0; i < NCH; ++i) { const int c = tid + 256 * i; *(u32x4*)((base) + (c >> 3) * 144 + (c & 7) * 16) = src[i]; }
; template <int WGN, int INS, int IMS, bool DB, class LdW, class LdX>
; DI void gemm_core(f32x16 (&acc)[INS][IMS], const int KT, LdW ldw, LdX ldx, char* lds, const int tid) {
;     ...
;   if (DB) {
;     u32x4 preA[NCH], preB[NCH];
;     GLOAD(preA, 0)
;     GLOAD(preB, 1)
;     __syncthreads();
;     LSTORE(preA, lds)
;     __syncthreads();
;     for (int kt = 0; kt < KT; kt += 2) {
;       if (kt + 2 < KT) { GLOAD(preA, kt + 2) }
;       COMPUTE_PIPE(lds)
;       LSTORE(preB, lds + BUFB)
;       __syncthreads();
;       if (kt + 3 < KT) { GLOAD(preB, kt + 3) }
;       COMPUTE_PIPE(lds + BUFB)
;       if (kt + 2 < KT) { LSTORE(preA, lds) }
;       __syncthreads();
;     }
	ds_read_b128 v[90:93], v64 offset:36864
	ds_read_b128 v[94:97], v67 offset:55296
	ds_read_b128 v[98:101], v64 offset:36896
	ds_read_b128 v[102:105], v67 offset:55328
	v_mfma_f32_32x32x16_bf16 v[0:15], v[130:133], v[134:137], v[0:15]
	ds_read_b128 v[106:109], v64 offset:41472
	ds_read_b128 v[130:133], v64 offset:41504
	s_waitcnt lgkmcnt(4)
	v_mfma_f32_32x32x16_bf16 v[48:63], v[90:93], v[94:97], v[48:63]
	s_waitcnt lgkmcnt(1)
	v_mfma_f32_32x32x16_bf16 v[32:47], v[106:109], v[94:97], v[32:47]
	ds_read_b128 v[94:97], v67 offset:59904
	ds_read_b128 v[134:137], v67 offset:59936
	s_waitcnt lgkmcnt(1)
	v_mfma_f32_32x32x16_bf16 v[16:31], v[90:93], v[94:97], v[16:31]
	v_mfma_f32_32x32x16_bf16 v[0:15], v[106:109], v[94:97], v[0:15]
	v_mfma_f32_32x32x16_bf16 v[48:63], v[98:101], v[102:105], v[48:63]
	v_mfma_f32_32x32x16_bf16 v[32:47], v[130:133], v[102:105], v[32:47]
	s_waitcnt lgkmcnt(0)
	v_mfma_f32_32x32x16_bf16 v[16:31], v[98:101], v[134:137], v[16:31]
	ds_read_b128 v[90:93], v64 offset:36928
	ds_read_b128 v[94:97], v67 offset:55360
	ds_read_b128 v[98:101], v64 offset:36960
	ds_read_b128 v[102:105], v67 offset:55392
	v_mfma_f32_32x32x16_bf16 v[0:15], v[130:133], v[134:137], v[0:15]
	ds_read_b128 v[106:109], v64 offset:41536
	ds_read_b128 v[130:133], v64 offset:41568
	s_waitcnt lgkmcnt(4)
	v_mfma_f32_32x32x16_bf16 v[48:63], v[90:93], v[94:97], v[48:63]
	s_waitcnt lgkmcnt(1)
	v_mfma_f32_32x32x16_bf16 v[32:47], v[106:109], v[94:97], v[32:47]
	ds_read_b128 v[94:97], v67 offset:59968
	ds_read_b128 v[134:137], v67 offset:60000
	s_waitcnt lgkmcnt(1)
	v_mfma_f32_32x32x16_bf16 v[16:31], v[90:93], v[94:97], v[16:31]
	v_or_b32_e32 v90, 0x240, v178
	v_mov_b32_e32 v91, v179
	v_lshlrev_b64 v[142:143], 1, v[90:91]
	v_lshl_add_u64 v[90:91], s[0:1], 0, v[142:143]
	v_lshl_add_u64 v[138:139], s[4:5], 0, v[142:143]
	v_lshl_add_u64 v[140:141], s[6:7], 0, v[142:143]
	v_lshl_add_u64 v[144:145], s[8:9], 0, v[142:143]
	v_mfma_f32_32x32x16_bf16 v[0:15], v[106:109], v[94:97], v[0:15]
	v_lshl_add_u64 v[94:95], s[2:3], 0, v[142:143]
	v_lshl_add_u64 v[146:147], s[10:11], 0, v[142:143]
	global_load_dwordx4 v[90:93], v[90:91], off
	s_nop 0
	global_load_dwordx4 v[94:97], v[94:95], off
	v_mfma_f32_32x32x16_bf16 v[48:63], v[98:101], v[102:105], v[48:63]
	v_mfma_f32_32x32x16_bf16 v[32:47], v[130:133], v[102:105], v[32:47]
	global_load_dwordx4 v[102:105], v[72:73], off offset:1152
	global_load_dwordx4 v[106:109], v[84:85], off offset:1152
	s_waitcnt lgkmcnt(0)
	v_mfma_f32_32x32x16_bf16 v[16:31], v[98:101], v[134:137], v[16:31]
	global_load_dwordx4 v[98:101], v[138:139], off
	s_nop 0
	global_load_dwordx4 v[138:141], v[140:141], off
	s_nop 0
	global_load_dwordx4 v[142:145], v[144:145], off
	s_nop 0
	global_load_dwordx4 v[146:149], v[146:147], off
	s_waitcnt vmcnt(13)
	ds_write_b128 v66, v[122:125]
	ds_write_b128 v68, v[110:113]
	ds_write_b128 v70, v[114:117]
	s_waitcnt vmcnt(11)
	ds_write_b128 v74, v[118:121]
	ds_write_b128 v76, v[126:129]
	s_waitcnt vmcnt(10)
	ds_write_b128 v78, v[150:153]
	s_waitcnt vmcnt(9)
	ds_write_b128 v80, v[154:157]
	s_waitcnt vmcnt(8)
	ds_write_b128 v82, v[158:161]
	s_waitcnt lgkmcnt(0)
	s_barrier
	ds_read_b128 v[110:113], v64
	ds_read_b128 v[114:117], v67 offset:18432
	ds_read_b128 v[118:121], v64 offset:32
	ds_read_b128 v[122:125], v67 offset:18464
	v_mfma_f32_32x32x16_bf16 v[0:15], v[130:133], v[134:137], v[0:15]
	ds_read_b128 v[126:129], v64 offset:4608
	ds_read_b128 v[130:133], v64 offset:4640
	s_waitcnt lgkmcnt(4)
	v_mfma_f32_32x32x16_bf16 v[48:63], v[110:113], v[114:117], v[48:63]
	s_waitcnt lgkmcnt(1)
	v_mfma_f32_32x32x16_bf16 v[32:47], v[126:129], v[114:117], v[32:47]
	ds_read_b128 v[114:117], v67 offset:23040
	ds_read_b128 v[134:137], v67 offset:23072
	s_waitcnt lgkmcnt(1)
	v_mfma_f32_32x32x16_bf16 v[16:31], v[110:113], v[114:117], v[16:31]
	v_mfma_f32_32x32x16_bf16 v[0:15], v[126:129], v[114:117], v[0:15]
	v_mfma_f32_32x32x16_bf16 v[48:63], v[118:121], v[122:125], v[48:63]
	v_mfma_f32_32x32x16_bf16 v[32:47], v[130:133], v[122:125], v[32:47]
	s_waitcnt lgkmcnt(0)
	v_mfma_f32_32x32x16_bf16 v[16:31], v[118:121], v[134:137], v[16:31]
	ds_read_b128 v[110:113], v64 offset:64
	ds_read_b128 v[114:117], v67 offset:18496
	ds_read_b128 v[118:121], v64 offset:96
	ds_read_b128 v[122:125], v67 offset:18528
	v_mfma_f32_32x32x16_bf16 v[0:15], v[130:133], v[134:137], v[0:15]
	ds_read_b128 v[126:129], v64 offset:4672
	ds_read_b128 v[130:133], v64 offset:4704
	s_waitcnt lgkmcnt(4)
	v_mfma_f32_32x32x16_bf16 v[48:63], v[110:113], v[114:117], v[48:63]
	s_waitcnt lgkmcnt(1)
	v_mfma_f32_32x32x16_bf16 v[32:47], v[126:129], v[114:117], v[32:47]
	ds_read_b128 v[114:117], v67 offset:23104
	ds_read_b128 v[134:137], v67 offset:23136
	s_waitcnt lgkmcnt(1)
	v_mfma_f32_32x32x16_bf16 v[16:31], v[110:113], v[114:117], v[16:31]
	v_or_b32_e32 v110, 0x280, v178
	v_mov_b32_e32 v111, v179
	v_lshlrev_b64 v[154:155], 1, v[110:111]
	v_lshl_add_u64 v[110:111], s[0:1], 0, v[154:155]
	v_lshl_add_u64 v[150:151], s[4:5], 0, v[154:155]
	v_lshl_add_u64 v[152:153], s[6:7], 0, v[154:155]
	v_lshl_add_u64 v[156:157], s[8:9], 0, v[154:155]
	v_mfma_f32_32x32x16_bf16 v[0:15], v[126:129], v[114:117], v[0:15]
	v_lshl_add_u64 v[114:115], s[2:3], 0, v[154:155]
	v_lshl_add_u64 v[158:159], s[10:11], 0, v[154:155]
	global_load_dwordx4 v[110:113], v[110:111], off
	s_nop 0
	global_load_dwordx4 v[114:117], v[114:115], off
	v_mfma_f32_32x32x16_bf16 v[48:63], v[118:121], v[122:125], v[48:63]
	v_mfma_f32_32x32x16_bf16 v[32:47], v[130:133], v[122:125], v[32:47]
	global_load_dwordx4 v[122:125], v[72:73], off offset:1280
	global_load_dwordx4 v[126:129], v[84:85], off offset:1280
	s_waitcnt lgkmcnt(0)
	v_mfma_f32_32x32x16_bf16 v[16:31], v[118:121], v[134:137], v[16:31]
	global_load_dwordx4 v[118:121], v[150:151], off
	s_nop 0
	global_load_dwordx4 v[150:153], v[152:153], off
	s_nop 0
	global_load_dwordx4 v[154:157], v[156:157], off
	s_nop 0
	global_load_dwordx4 v[158:161], v[158:159], off
	s_waitcnt vmcnt(13)
	ds_write_b128 v66, v[102:105] offset:36864
	ds_write_b128 v68, v[90:93] offset:36864
	ds_write_b128 v70, v[94:97] offset:36864
	s_waitcnt vmcnt(11)
	ds_write_b128 v74, v[98:101] offset:36864
	ds_write_b128 v76, v[106:109] offset:36864
	s_waitcnt vmcnt(10)
	ds_write_b128 v78, v[138:141] offset:36864
	s_waitcnt vmcnt(9)
	ds_write_b128 v80, v[142:145] offset:36864
	s_waitcnt vmcnt(8)
	ds_write_b128 v82, v[146:149] offset:36864
	s_waitcnt lgkmcnt(0)
	s_barrier
; #define GLOAD(dst, kt_) _Pragma("unroll") for (int i = 0; i < NCH; ++i) { dst[i] = (i < NCHW) ? ldw(i, tid >> 3, (kt_) * 64 + (tid & 7) * 8) : ldx(i - NCHW, tid >> 3, (kt_) * 64 + (tid & 7) * 8); }
; #define LSTORE(src, base) _Pragma("unroll") for (int i = 0; i < NCH; ++i) { const int c = tid + 256 * i; *(u32x4*)((base) + (c >> 3) * 144 + (c & 7) * 16) = src[i]; }
; template <int WGN, int INS, int IMS, bool DB, class LdW, class LdX>
; DI void gemm_core(f32x16 (&acc)[INS][IMS], const int KT, LdW ldw, LdX ldx, char* lds, const int tid) {
;     ...
;   if (DB) {
;     u32x4 preA[NCH], preB[NCH];
;     GLOAD(preA, 0)
;     GLOAD(preB, 1)
;     __syncthreads();
;     LSTORE(preA, lds)
;     __syncthreads();
;     for (int kt = 0; kt < KT; kt += 2) {
;       if (kt + 2 < KT) { GLOAD(preA, kt + 2) }
;       COMPUTE_PIPE(lds)
;       LSTORE(preB, lds + BUFB)
;       __syncthreads();
;       if (kt + 3 < KT) { GLOAD(preB, kt + 3) }
;       COMPUTE_PIPE(lds + BUFB)
;       if (kt + 2 < KT) { LSTORE(preA, lds) }
;       __syncthreads();
;     }
	ds_read_b128 v[90:93], v64 offset:36864
	ds_read_b128 v[94:97], v67 offset:55296
	ds_read_b128 v[98:101], v64 offset:36896
	ds_read_b128 v[102:105], v67 offset:55328
	v_mfma_f32_32x32x16_bf16 v[0:15], v[130:133], v[134:137], v[0:15]
	ds_read_b128 v[106:109], v64 offset:41472
	ds_read_b128 v[130:133], v64 offset:41504
	s_waitcnt lgkmcnt(4)
	v_mfma_f32_32x32x16_bf16 v[48:63], v[90:93], v[94:97], v[48:63]
	s_waitcnt lgkmcnt(1)
	v_mfma_f32_32x32x16_bf16 v[32:47], v[106:109], v[94:97], v[32:47]
	ds_read_b128 v[94:97], v67 offset:59904
	ds_read_b128 v[134:137], v67 offset:59936
	s_waitcnt lgkmcnt(1)
	v_mfma_f32_32x32x16_bf16 v[16:31], v[90:93], v[94:97], v[16:31]
	v_mfma_f32_32x32x16_bf16 v[0:15], v[106:109], v[94:97], v[0:15]
	v_mfma_f32_32x32x16_bf16 v[48:63], v[98:101], v[102:105], v[48:63]
	v_mfma_f32_32x32x16_bf16 v[32:47], v[130:133], v[102:105], v[32:47]
	s_waitcnt lgkmcnt(0)
	v_mfma_f32_32x32x16_bf16 v[16:31], v[98:101], v[134:137], v[16:31]
	ds_read_b128 v[90:93], v64 offset:36928
	ds_read_b128 v[94:97], v67 offset:55360
	ds_read_b128 v[98:101], v64 offset:36960
	ds_read_b128 v[102:105], v67 offset:55392
	v_mfma_f32_32x32x16_bf16 v[0:15], v[130:133], v[134:137], v[0:15]
	ds_read_b128 v[106:109], v64 offset:41536
	ds_read_b128 v[130:133], v64 offset:41568
	s_waitcnt lgkmcnt(4)
	v_mfma_f32_32x32x16_bf16 v[48:63], v[90:93], v[94:97], v[48:63]
	s_waitcnt lgkmcnt(1)
	v_mfma_f32_32x32x16_bf16 v[32:47], v[106:109], v[94:97], v[32:47]
	ds_read_b128 v[94:97], v67 offset:59968
	ds_read_b128 v[134:137], v67 offset:60000
	s_waitcnt lgkmcnt(1)
	v_mfma_f32_32x32x16_bf16 v[16:31], v[90:93], v[94:97], v[16:31]
	v_or_b32_e32 v90, 0x2c0, v178
	v_mov_b32_e32 v91, v179
	v_lshlrev_b64 v[142:143], 1, v[90:91]
	v_lshl_add_u64 v[90:91], s[0:1], 0, v[142:143]
	v_lshl_add_u64 v[138:139], s[4:5], 0, v[142:143]
	v_lshl_add_u64 v[140:141], s[6:7], 0, v[142:143]
	v_lshl_add_u64 v[144:145], s[8:9], 0, v[142:143]
	v_mfma_f32_32x32x16_bf16 v[0:15], v[106:109], v[94:97], v[0:15]
	v_lshl_add_u64 v[94:95], s[2:3], 0, v[142:143]
	v_lshl_add_u64 v[146:147], s[10:11], 0, v[142:143]
	global_load_dwordx4 v[90:93], v[90:91], off
	s_nop 0
	global_load_dwordx4 v[94:97], v[94:95], off
	v_mfma_f32_32x32x16_bf16 v[48:63], v[98:101], v[102:105], v[48:63]
	v_mfma_f32_32x32x16_bf16 v[32:47], v[130:133], v[102:105], v[32:47]
	global_load_dwordx4 v[102:105], v[72:73], off offset:1408
	global_load_dwordx4 v[106:109], v[84:85], off offset:1408
	s_waitcnt lgkmcnt(0)
	v_mfma_f32_32x32x16_bf16 v[16:31], v[98:101], v[134:137], v[16:31]
	global_load_dwordx4 v[98:101], v[138:139], off
	s_nop 0
	global_load_dwordx4 v[138:141], v[140:141], off
	s_nop 0
	global_load_dwordx4 v[142:145], v[144:145], off
	s_nop 0
	global_load_dwordx4 v[146:149], v[146:147], off
	s_waitcnt vmcnt(13)
	ds_write_b128 v66, v[122:125]
	ds_write_b128 v68, v[110:113]
	ds_write_b128 v70, v[114:117]
	s_waitcnt vmcnt(11)
	ds_write_b128 v74, v[118:121]
	ds_write_b128 v76, v[126:129]
	s_waitcnt vmcnt(10)
	ds_write_b128 v78, v[150:153]
	s_waitcnt vmcnt(9)
	ds_write_b128 v80, v[154:157]
	s_waitcnt vmcnt(8)
	ds_write_b128 v82, v[158:161]
	s_waitcnt lgkmcnt(0)
	s_barrier
	ds_read_b128 v[110:113], v64
	ds_read_b128 v[114:117], v67 offset:18432
	ds_read_b128 v[118:121], v64 offset:32
	ds_read_b128 v[122:125], v67 offset:18464
	v_mfma_f32_32x32x16_bf16 v[0:15], v[130:133], v[134:137], v[0:15]
	ds_read_b128 v[126:129], v64 offset:4608
	ds_read_b128 v[130:133], v64 offset:4640
	s_waitcnt lgkmcnt(4)
	v_mfma_f32_32x32x16_bf16 v[48:63], v[110:113], v[114:117], v[48:63]
	s_waitcnt lgkmcnt(1)
	v_mfma_f32_32x32x16_bf16 v[32:47], v[126:129], v[114:117], v[32:47]
	ds_read_b128 v[114:117], v67 offset:23040
	ds_read_b128 v[134:137], v67 offset:23072
	s_waitcnt lgkmcnt(1)
	v_mfma_f32_32x32x16_bf16 v[16:31], v[110:113], v[114:117], v[16:31]
	v_mfma_f32_32x32x16_bf16 v[0:15], v[126:129], v[114:117], v[0:15]
	v_mfma_f32_32x32x16_bf16 v[48:63], v[118:121], v[122:125], v[48:63]
	v_mfma_f32_32x32x16_bf16 v[32:47], v[130:133], v[122:125], v[32:47]
	s_waitcnt lgkmcnt(0)
	v_mfma_f32_32x32x16_bf16 v[16:31], v[118:121], v[134:137], v[16:31]
	ds_read_b128 v[110:113], v64 offset:64
	ds_read_b128 v[114:117], v67 offset:18496
	ds_read_b128 v[118:121], v64 offset:96
	ds_read_b128 v[122:125], v67 offset:18528
	v_mfma_f32_32x32x16_bf16 v[0:15], v[130:133], v[134:137], v[0:15]
	ds_read_b128 v[126:129], v64 offset:4672
	ds_read_b128 v[130:133], v64 offset:4704
	s_waitcnt lgkmcnt(4)
	v_mfma_f32_32x32x16_bf16 v[48:63], v[110:113], v[114:117], v[48:63]
	s_waitcnt lgkmcnt(1)
	v_mfma_f32_32x32x16_bf16 v[32:47], v[126:129], v[114:117], v[32:47]
	ds_read_b128 v[114:117], v67 offset:23104
	ds_read_b128 v[134:137], v67 offset:23136
	s_waitcnt lgkmcnt(1)
	v_mfma_f32_32x32x16_bf16 v[16:31], v[110:113], v[114:117], v[16:31]
	v_or_b32_e32 v110, 0x300, v178
	v_mov_b32_e32 v111, v179
	v_lshlrev_b64 v[154:155], 1, v[110:111]
	v_lshl_add_u64 v[110:111], s[0:1], 0, v[154:155]
	v_lshl_add_u64 v[150:151], s[4:5], 0, v[154:155]
	v_lshl_add_u64 v[152:153], s[6:7], 0, v[154:155]
	v_lshl_add_u64 v[156:157], s[8:9], 0, v[154:155]
	v_mfma_f32_32x32x16_bf16 v[0:15], v[126:129], v[114:117], v[0:15]
	v_lshl_add_u64 v[114:115], s[2:3], 0, v[154:155]
	v_lshl_add_u64 v[158:159], s[10:11], 0, v[154:155]
	global_load_dwordx4 v[110:113], v[110:111], off
	s_nop 0
	global_load_dwordx4 v[114:117], v[114:115], off
	v_mfma_f32_32x32x16_bf16 v[48:63], v[118:121], v[122:125], v[48:63]
	v_mfma_f32_32x32x16_bf16 v[32:47], v[130:133], v[122:125], v[32:47]
	global_load_dwordx4 v[122:125], v[72:73], off offset:1536
	global_load_dwordx4 v[126:129], v[84:85], off offset:1536
	s_waitcnt lgkmcnt(0)
	v_mfma_f32_32x32x16_bf16 v[16:31], v[118:121], v[134:137], v[16:31]
	global_load_dwordx4 v[118:121], v[150:151], off
	s_nop 0
	global_load_dwordx4 v[150:153], v[152:153], off
	s_nop 0
	global_load_dwordx4 v[154:157], v[156:157], off
	s_nop 0
	global_load_dwordx4 v[158:161], v[158:159], off
	s_waitcnt vmcnt(13)
	ds_write_b128 v66, v[102:105] offset:36864
	ds_write_b128 v68, v[90:93] offset:36864
	ds_write_b128 v70, v[94:97] offset:36864
	s_waitcnt vmcnt(11)
	ds_write_b128 v74, v[98:101] offset:36864
	ds_write_b128 v76, v[106:109] offset:36864
	s_waitcnt vmcnt(10)
	ds_write_b128 v78, v[138:141] offset:36864
	s_waitcnt vmcnt(9)
	ds_write_b128 v80, v[142:145] offset:36864
	s_waitcnt vmcnt(8)
	ds_write_b128 v82, v[146:149] offset:36864
	s_waitcnt lgkmcnt(0)
	s_barrier
; #define GLOAD(dst, kt_) _Pragma("unroll") for (int i = 0; i < NCH; ++i) { dst[i] = (i < NCHW) ? ldw(i, tid >> 3, (kt_) * 64 + (tid & 7) * 8) : ldx(i - NCHW, tid >> 3, (kt_) * 64 + (tid & 7) * 8); }
; #define LSTORE(src, base) _Pragma("unroll") for (int i = 0; i < NCH; ++i) { const int c = tid + 256 * i; *(u32x4*)((base) + (c >> 3) * 144 + (c & 7) * 16) = src[i]; }
; template <int WGN, int INS, int IMS, bool DB, class LdW, class LdX>
; DI void gemm_core(f32x16 (&acc)[INS][IMS], const int KT, LdW ldw, LdX ldx, char* lds, const int tid) {
;     ...
;   if (DB) {
;     u32x4 preA[NCH], preB[NCH];
;     GLOAD(preA, 0)
;     GLOAD(preB, 1)
;     __syncthreads();
;     LSTORE(preA, lds)
;     __syncthreads();
;     for (int kt = 0; kt < KT; kt += 2) {
;       if (kt + 2 < KT) { GLOAD(preA, kt + 2) }
;       COMPUTE_PIPE(lds)
;       LSTORE(preB, lds + BUFB)
;       __syncthreads();
;       if (kt + 3 < KT) { GLOAD(preB, kt + 3) }
;       COMPUTE_PIPE(lds + BUFB)
;       if (kt + 2 < KT) { LSTORE(preA, lds) }
;       __syncthreads();
;     }
	ds_read_b128 v[90:93], v64 offset:36864
	ds_read_b128 v[94:97], v67 offset:55296
	ds_read_b128 v[98:101], v64 offset:36896
	ds_read_b128 v[102:105], v67 offset:55328
	v_mfma_f32_32x32x16_bf16 v[0:15], v[130:133], v[134:137], v[0:15]
	ds_read_b128 v[106:109], v64 offset:41472
	ds_read_b128 v[130:133], v64 offset:41504
	s_waitcnt lgkmcnt(4)
	v_mfma_f32_32x32x16_bf16 v[48:63], v[90:93], v[94:97], v[48:63]
	s_waitcnt lgkmcnt(1)
	v_mfma_f32_32x32x16_bf16 v[32:47], v[106:109], v[94:97], v[32:47]
	ds_read_b128 v[94:97], v67 offset:59904
	ds_read_b128 v[134:137], v67 offset:59936
	s_waitcnt lgkmcnt(1)
	v_mfma_f32_32x32x16_bf16 v[16:31], v[90:93], v[94:97], v[16:31]
	v_mfma_f32_32x32x16_bf16 v[0:15], v[106:109], v[94:97], v[0:15]
	v_mfma_f32_32x32x16_bf16 v[48:63], v[98:101], v[102:105], v[48:63]
	v_mfma_f32_32x32x16_bf16 v[32:47], v[130:133], v[102:105], v[32:47]
	s_waitcnt lgkmcnt(0)
	v_mfma_f32_32x32x16_bf16 v[16:31], v[98:101], v[134:137], v[16:31]
	ds_read_b128 v[90:93], v64 offset:36928
	ds_read_b128 v[94:97], v67 offset:55360
	ds_read_b128 v[98:101], v64 offset:36960
	ds_read_b128 v[102:105], v67 offset:55392
	v_mfma_f32_32x32x16_bf16 v[0:15], v[130:133], v[134:137], v[0:15]
	ds_read_b128 v[106:109], v64 offset:41536
	ds_read_b128 v[130:133], v64 offset:41568
	s_waitcnt lgkmcnt(4)
	v_mfma_f32_32x32x16_bf16 v[48:63], v[90:93], v[94:97], v[48:63]
	s_waitcnt lgkmcnt(1)
	v_mfma_f32_32x32x16_bf16 v[32:47], v[106:109], v[94:97], v[32:47]
	ds_read_b128 v[94:97], v67 offset:59968
	ds_read_b128 v[134:137], v67 offset:60000
	s_waitcnt lgkmcnt(1)
	v_mfma_f32_32x32x16_bf16 v[16:31], v[90:93], v[94:97], v[16:31]
	v_or_b32_e32 v90, 0x340, v178
	v_mov_b32_e32 v91, v179
	v_lshlrev_b64 v[142:143], 1, v[90:91]
	v_lshl_add_u64 v[90:91], s[0:1], 0, v[142:143]
	v_lshl_add_u64 v[138:139], s[4:5], 0, v[142:143]
	v_lshl_add_u64 v[140:141], s[6:7], 0, v[142:143]
	v_lshl_add_u64 v[144:145], s[8:9], 0, v[142:143]
	v_mfma_f32_32x32x16_bf16 v[0:15], v[106:109], v[94:97], v[0:15]
	v_lshl_add_u64 v[94:95], s[2:3], 0, v[142:143]
	v_lshl_add_u64 v[146:147], s[10:11], 0, v[142:143]
	global_load_dwordx4 v[90:93], v[90:91], off
	s_nop 0
	global_load_dwordx4 v[94:97], v[94:95], off
	v_mfma_f32_32x32x16_bf16 v[48:63], v[98:101], v[102:105], v[48:63]
	v_mfma_f32_32x32x16_bf16 v[32:47], v[130:133], v[102:105], v[32:47]
	global_load_dwordx4 v[102:105], v[72:73], off offset:1664
	global_load_dwordx4 v[106:109], v[84:85], off offset:1664
	s_waitcnt lgkmcnt(0)
	v_mfma_f32_32x32x16_bf16 v[16:31], v[98:101], v[134:137], v[16:31]
	global_load_dwordx4 v[98:101], v[138:139], off
	s_nop 0
	global_load_dwordx4 v[138:141], v[140:141], off
	s_nop 0
	global_load_dwordx4 v[142:145], v[144:145], off
	s_nop 0
	global_load_dwordx4 v[146:149], v[146:147], off
	s_waitcnt vmcnt(13)
	ds_write_b128 v66, v[122:125]
	ds_write_b128 v68, v[110:113]
	ds_write_b128 v70, v[114:117]
	s_waitcnt vmcnt(11)
	ds_write_b128 v74, v[118:121]
	ds_write_b128 v76, v[126:129]
	s_waitcnt vmcnt(10)
	ds_write_b128 v78, v[150:153]
	s_waitcnt vmcnt(9)
	ds_write_b128 v80, v[154:157]
	s_waitcnt vmcnt(8)
	ds_write_b128 v82, v[158:161]
	s_waitcnt lgkmcnt(0)
	s_barrier
	ds_read_b128 v[110:113], v64
	ds_read_b128 v[114:117], v67 offset:18432
	ds_read_b128 v[118:121], v64 offset:32
	ds_read_b128 v[122:125], v67 offset:18464
	v_mfma_f32_32x32x16_bf16 v[0:15], v[130:133], v[134:137], v[0:15]
	ds_read_b128 v[126:129], v64 offset:4608
	ds_read_b128 v[130:133], v64 offset:4640
	s_waitcnt lgkmcnt(4)
	v_mfma_f32_32x32x16_bf16 v[48:63], v[110:113], v[114:117], v[48:63]
	s_waitcnt lgkmcnt(1)
	v_mfma_f32_32x32x16_bf16 v[32:47], v[126:129], v[114:117], v[32:47]
	ds_read_b128 v[114:117], v67 offset:23040
	ds_read_b128 v[134:137], v67 offset:23072
	s_waitcnt lgkmcnt(1)
	v_mfma_f32_32x32x16_bf16 v[16:31], v[110:113], v[114:117], v[16:31]
	v_mfma_f32_32x32x16_bf16 v[0:15], v[126:129], v[114:117], v[0:15]
	v_mfma_f32_32x32x16_bf16 v[48:63], v[118:121], v[122:125], v[48:63]
	v_mfma_f32_32x32x16_bf16 v[32:47], v[130:133], v[122:125], v[32:47]
	s_waitcnt lgkmcnt(0)
	v_mfma_f32_32x32x16_bf16 v[16:31], v[118:121], v[134:137], v[16:31]
	ds_read_b128 v[110:113], v64 offset:64
	ds_read_b128 v[114:117], v67 offset:18496
	ds_read_b128 v[118:121], v64 offset:96
	ds_read_b128 v[122:125], v67 offset:18528
	v_mfma_f32_32x32x16_bf16 v[0:15], v[130:133], v[134:137], v[0:15]
	ds_read_b128 v[126:129], v64 offset:4672
	ds_read_b128 v[130:133], v64 offset:4704
	s_waitcnt lgkmcnt(4)
	v_mfma_f32_32x32x16_bf16 v[48:63], v[110:113], v[114:117], v[48:63]
	s_waitcnt lgkmcnt(1)
	v_mfma_f32_32x32x16_bf16 v[32:47], v[126:129], v[114:117], v[32:47]
	ds_read_b128 v[114:117], v67 offset:23104
	ds_read_b128 v[134:137], v67 offset:23136
	s_waitcnt lgkmcnt(1)
	v_mfma_f32_32x32x16_bf16 v[16:31], v[110:113], v[114:117], v[16:31]
	v_or_b32_e32 v110, 0x380, v178
	v_mov_b32_e32 v111, v179
	v_lshlrev_b64 v[154:155], 1, v[110:111]
	v_lshl_add_u64 v[110:111], s[0:1], 0, v[154:155]
	v_lshl_add_u64 v[150:151], s[4:5], 0, v[154:155]
	v_lshl_add_u64 v[152:153], s[6:7], 0, v[154:155]
	v_lshl_add_u64 v[156:157], s[8:9], 0, v[154:155]
	v_mfma_f32_32x32x16_bf16 v[0:15], v[126:129], v[114:117], v[0:15]
	v_lshl_add_u64 v[114:115], s[2:3], 0, v[154:155]
	v_lshl_add_u64 v[158:159], s[10:11], 0, v[154:155]
	global_load_dwordx4 v[110:113], v[110:111], off
	s_nop 0
	global_load_dwordx4 v[114:117], v[114:115], off
	v_or_b32_e32 v178, 0x3c0, v178
	v_mfma_f32_32x32x16_bf16 v[48:63], v[118:121], v[122:125], v[48:63]
	v_mfma_f32_32x32x16_bf16 v[32:47], v[130:133], v[122:125], v[32:47]
	global_load_dwordx4 v[122:125], v[72:73], off offset:1792
	global_load_dwordx4 v[126:129], v[84:85], off offset:1792
	s_waitcnt lgkmcnt(0)
	v_mfma_f32_32x32x16_bf16 v[16:31], v[118:121], v[134:137], v[16:31]
	global_load_dwordx4 v[118:121], v[150:151], off
	s_nop 0
	global_load_dwordx4 v[150:153], v[152:153], off
	s_nop 0
	global_load_dwordx4 v[154:157], v[156:157], off
	s_nop 0
	global_load_dwordx4 v[158:161], v[158:159], off
	s_waitcnt vmcnt(13)
	ds_write_b128 v66, v[102:105] offset:36864
	ds_write_b128 v68, v[90:93] offset:36864
	ds_write_b128 v70, v[94:97] offset:36864
	s_waitcnt vmcnt(11)
	ds_write_b128 v74, v[98:101] offset:36864
	ds_write_b128 v76, v[106:109] offset:36864
	s_waitcnt vmcnt(10)
	ds_write_b128 v78, v[138:141] offset:36864
	s_waitcnt vmcnt(9)
	ds_write_b128 v80, v[142:145] offset:36864
	s_waitcnt vmcnt(8)
	ds_write_b128 v82, v[146:149] offset:36864
	s_waitcnt lgkmcnt(0)
	s_barrier
; #define GLOAD(dst, kt_) _Pragma("unroll") for (int i = 0; i < NCH; ++i) { dst[i] = (i < NCHW) ? ldw(i, tid >> 3, (kt_) * 64 + (tid & 7) * 8) : ldx(i - NCHW, tid >> 3, (kt_) * 64 + (tid & 7) * 8); }
; #define LSTORE(src, base) _Pragma("unroll") for (int i = 0; i < NCH; ++i) { const int c = tid + 256 * i; *(u32x4*)((base) + (c >> 3) * 144 + (c & 7) * 16) = src[i]; }
; template <int WGN, int INS, int IMS, bool DB, class LdW, class LdX>
; DI void gemm_core(f32x16 (&acc)[INS][IMS], const int KT, LdW ldw, LdX ldx, char* lds, const int tid) {
;     ...
;   if (DB) {
;     u32x4 preA[NCH], preB[NCH];
;     GLOAD(preA, 0)
;     GLOAD(preB, 1)
;     __syncthreads();
;     LSTORE(preA, lds)
;     __syncthreads();
;     for (int kt = 0; kt < KT; kt += 2) {
;       if (kt + 2 < KT) { GLOAD(preA, kt + 2) }
;       COMPUTE_PIPE(lds)
;       LSTORE(preB, lds + BUFB)
;       __syncthreads();
;       if (kt + 3 < KT) { GLOAD(preB, kt + 3) }
;       COMPUTE_PIPE(lds + BUFB)
;       if (kt + 2 < KT) { LSTORE(preA, lds) }
;       __syncthreads();
;     }
	ds_read_b128 v[90:93], v64 offset:36864
	ds_read_b128 v[94:97], v67 offset:55296
	ds_read_b128 v[98:101], v64 offset:36896
	ds_read_b128 v[102:105], v67 offset:55328
	v_mfma_f32_32x32x16_bf16 v[0:15], v[130:133], v[134:137], v[0:15]
	ds_read_b128 v[106:109], v64 offset:41472
	ds_read_b128 v[130:133], v64 offset:41504
	v_lshlrev_b64 v[142:143], 1, v[178:179]
	v_lshl_add_u64 v[138:139], s[4:5], 0, v[142:143]
	s_waitcnt lgkmcnt(4)
	v_mfma_f32_32x32x16_bf16 v[48:63], v[90:93], v[94:97], v[48:63]
	s_waitcnt lgkmcnt(1)
	v_mfma_f32_32x32x16_bf16 v[32:47], v[106:109], v[94:97], v[32:47]
	ds_read_b128 v[94:97], v67 offset:59904
	ds_read_b128 v[134:137], v67 offset:59936
	s_waitcnt lgkmcnt(1)
	v_mfma_f32_32x32x16_bf16 v[16:31], v[90:93], v[94:97], v[16:31]
	v_mfma_f32_32x32x16_bf16 v[0:15], v[106:109], v[94:97], v[0:15]
	v_mfma_f32_32x32x16_bf16 v[48:63], v[98:101], v[102:105], v[48:63]
	v_mfma_f32_32x32x16_bf16 v[32:47], v[130:133], v[102:105], v[32:47]
	s_waitcnt lgkmcnt(0)
	v_mfma_f32_32x32x16_bf16 v[16:31], v[98:101], v[134:137], v[16:31]
	ds_read_b128 v[90:93], v64 offset:36928
	ds_read_b128 v[94:97], v67 offset:55360
	ds_read_b128 v[98:101], v64 offset:36960
	ds_read_b128 v[102:105], v67 offset:55392
	v_mfma_f32_32x32x16_bf16 v[0:15], v[130:133], v[134:137], v[0:15]
	ds_read_b128 v[106:109], v64 offset:41536
	ds_read_b128 v[130:133], v64 offset:41568
	s_waitcnt lgkmcnt(4)
	v_mfma_f32_32x32x16_bf16 v[48:63], v[90:93], v[94:97], v[48:63]
	s_waitcnt lgkmcnt(1)
	v_mfma_f32_32x32x16_bf16 v[32:47], v[106:109], v[94:97], v[32:47]
	ds_read_b128 v[94:97], v67 offset:59968
	ds_read_b128 v[134:137], v67 offset:60000
	s_waitcnt lgkmcnt(1)
	v_mfma_f32_32x32x16_bf16 v[16:31], v[90:93], v[94:97], v[16:31]
	v_lshl_add_u64 v[90:91], s[0:1], 0, v[142:143]
	s_add_u32 s0, s12, 0x4a40000
	s_addc_u32 s1, s13, 0
	v_mfma_f32_32x32x16_bf16 v[0:15], v[106:109], v[94:97], v[0:15]
	v_lshl_add_u64 v[94:95], s[2:3], 0, v[142:143]
	global_load_dwordx4 v[90:93], v[90:91], off
	s_nop 0
	global_load_dwordx4 v[94:97], v[94:95], off
	s_mov_b32 s2, 0
	v_mfma_f32_32x32x16_bf16 v[48:63], v[98:101], v[102:105], v[48:63]
	v_mfma_f32_32x32x16_bf16 v[32:47], v[130:133], v[102:105], v[32:47]
	global_load_dwordx4 v[102:105], v[72:73], off offset:1920
	global_load_dwordx4 v[106:109], v[84:85], off offset:1920
	v_lshl_add_u64 v[72:73], s[6:7], 0, v[142:143]
	v_lshl_add_u64 v[84:85], s[10:11], 0, v[142:143]
	s_waitcnt lgkmcnt(0)
	v_mfma_f32_32x32x16_bf16 v[16:31], v[98:101], v[134:137], v[16:31]
	global_load_dwordx4 v[98:101], v[138:139], off
	s_nop 0
	global_load_dwordx4 v[138:141], v[72:73], off
	v_lshl_add_u64 v[72:73], s[8:9], 0, v[142:143]
	global_load_dwordx4 v[142:145], v[72:73], off
	global_load_dwordx4 v[146:149], v[84:85], off
	s_waitcnt vmcnt(13)
	ds_write_b128 v66, v[122:125]
	ds_write_b128 v68, v[110:113]
	ds_write_b128 v70, v[114:117]
	s_waitcnt vmcnt(11)
	ds_write_b128 v74, v[118:121]
	ds_write_b128 v76, v[126:129]
	s_waitcnt vmcnt(10)
	ds_write_b128 v78, v[150:153]
	s_waitcnt vmcnt(9)
	ds_write_b128 v80, v[154:157]
	s_waitcnt vmcnt(8)
	ds_write_b128 v82, v[158:161]
	s_waitcnt lgkmcnt(0)
	s_barrier
	v_mfma_f32_32x32x16_bf16 v[0:15], v[130:133], v[134:137], v[0:15]
	ds_read_b128 v[110:113], v64
	ds_read_b128 v[114:117], v67 offset:18432
	ds_read_b128 v[118:121], v64 offset:32
	ds_read_b128 v[122:125], v67 offset:18464
	ds_read_b128 v[126:129], v64 offset:4608
	ds_read_b128 v[130:133], v64 offset:4640
	s_waitcnt lgkmcnt(4)
	v_mfma_f32_32x32x16_bf16 v[48:63], v[110:113], v[114:117], v[48:63]
	s_waitcnt lgkmcnt(1)
	v_mfma_f32_32x32x16_bf16 v[32:47], v[126:129], v[114:117], v[32:47]
	ds_read_b128 v[114:117], v67 offset:23040
	ds_read_b128 v[134:137], v67 offset:23072
	s_waitcnt lgkmcnt(1)
	v_mfma_f32_32x32x16_bf16 v[16:31], v[110:113], v[114:117], v[16:31]
	v_mfma_f32_32x32x16_bf16 v[0:15], v[126:129], v[114:117], v[0:15]
	v_mfma_f32_32x32x16_bf16 v[48:63], v[118:121], v[122:125], v[48:63]
	v_mfma_f32_32x32x16_bf16 v[32:47], v[130:133], v[122:125], v[32:47]
	s_waitcnt lgkmcnt(0)
	v_mfma_f32_32x32x16_bf16 v[16:31], v[118:121], v[134:137], v[16:31]
	ds_read_b128 v[110:113], v64 offset:64
	ds_read_b128 v[114:117], v67 offset:18496
	ds_read_b128 v[118:121], v64 offset:96
	ds_read_b128 v[122:125], v67 offset:18528
	v_mfma_f32_32x32x16_bf16 v[0:15], v[130:133], v[134:137], v[0:15]
	ds_read_b128 v[126:129], v64 offset:4672
	ds_read_b128 v[130:133], v64 offset:4704
	s_waitcnt lgkmcnt(4)
	v_mfma_f32_32x32x16_bf16 v[48:63], v[110:113], v[114:117], v[48:63]
	s_waitcnt lgkmcnt(1)
	v_mfma_f32_32x32x16_bf16 v[32:47], v[126:129], v[114:117], v[32:47]
	ds_read_b128 v[114:117], v67 offset:23104
	ds_read_b128 v[134:137], v67 offset:23136
	s_waitcnt vmcnt(5)
	ds_write_b128 v66, v[102:105] offset:36864
	ds_write_b128 v68, v[90:93] offset:36864
	ds_write_b128 v70, v[94:97] offset:36864
	s_waitcnt vmcnt(3)
	ds_write_b128 v74, v[98:101] offset:36864
	ds_write_b128 v76, v[106:109] offset:36864
	s_waitcnt vmcnt(2)
	ds_write_b128 v78, v[138:141] offset:36864
	s_waitcnt vmcnt(1)
	ds_write_b128 v80, v[142:145] offset:36864
	s_waitcnt vmcnt(0)
	ds_write_b128 v82, v[146:149] offset:36864
	s_waitcnt lgkmcnt(0)
	s_barrier
; #define GLOAD(dst, kt_) _Pragma("unroll") for (int i = 0; i < NCH; ++i) { dst[i] = (i < NCHW) ? ldw(i, tid >> 3, (kt_) * 64 + (tid & 7) * 8) : ldx(i - NCHW, tid >> 3, (kt_) * 64 + (tid & 7) * 8); }
; #define LSTORE(src, base) _Pragma("unroll") for (int i = 0; i < NCH; ++i) { const int c = tid + 256 * i; *(u32x4*)((base) + (c >> 3) * 144 + (c & 7) * 16) = src[i]; }
; template <int WGN, int INS, int IMS, bool DB, class LdW, class LdX>
; DI void gemm_core(f32x16 (&acc)[INS][IMS], const int KT, LdW ldw, LdX ldx, char* lds, const int tid) {
;     ...
;       COMPUTE_PIPE(lds)
;       LSTORE(preB, lds + BUFB)
;       __syncthreads();
;       if (kt + 3 < KT) { GLOAD(preB, kt + 3) }
;       COMPUTE_PIPE(lds + BUFB)
;       if (kt + 2 < KT) { LSTORE(preA, lds) }
;       __syncthreads();
;     }
; template <int NTW>
; DI void inproj_tile(const Params& p, int l, int mt, int ntile, char* lds) {
;     ...
;   __syncthreads();
; #pragma unroll
;   for (int im = 0; im < 2; ++im) {
;     const int tl = wm * 64 + im * 32 + l31;
;     const float r = rn[(size_t)mt * 128 + tl];
; #pragma unroll
;     for (int in = 0; in < NTW; ++in)
; #pragma unroll
;       for (int g = 0; g < 4; ++g) {
;         const int n = wn * 32 * NTW + in * 32 + 8 * g + 4 * hi;
;         u32x2 o; o[0] = pk2(acc[in][im][4 * g] * r, acc[in][im][4 * g + 1] * r); o[1] = pk2(acc[in][im][4 * g + 2] * r, acc[in][im][4 * g + 3] * r);
;         *(u32x2*)(lds + tl * RS + n * 2) = o;
;       }
;   }
	ds_read_b128 v[68:71], v64 offset:36864
	ds_read_b128 v[72:75], v67 offset:55296
	ds_read_b128 v[76:79], v64 offset:36896
	ds_read_b128 v[80:83], v67 offset:55328
	v_mfma_f32_32x32x16_bf16 v[16:31], v[110:113], v[114:117], v[16:31]
	ds_read_b128 v[90:93], v64 offset:41472
	ds_read_b128 v[94:97], v64 offset:41504
	v_mfma_f32_32x32x16_bf16 v[0:15], v[126:129], v[114:117], v[0:15]
	v_mfma_f32_32x32x16_bf16 v[48:63], v[118:121], v[122:125], v[48:63]
	v_mfma_f32_32x32x16_bf16 v[32:47], v[130:133], v[122:125], v[32:47]
	v_mfma_f32_32x32x16_bf16 v[16:31], v[118:121], v[134:137], v[16:31]
	v_mfma_f32_32x32x16_bf16 v[0:15], v[130:133], v[134:137], v[0:15]
	s_waitcnt lgkmcnt(4)
	v_mfma_f32_32x32x16_bf16 v[48:63], v[68:71], v[72:75], v[48:63]
	s_waitcnt lgkmcnt(1)
	v_mfma_f32_32x32x16_bf16 v[32:47], v[90:93], v[72:75], v[32:47]
	ds_read_b128 v[72:75], v67 offset:59904
	ds_read_b128 v[98:101], v67 offset:59936
	s_waitcnt lgkmcnt(1)
	v_mfma_f32_32x32x16_bf16 v[16:31], v[68:71], v[72:75], v[16:31]
	ds_read_b128 v[68:71], v64 offset:36928
	ds_read_b128 v[102:105], v64 offset:36960
	ds_read_b128 v[106:109], v64 offset:41536
	ds_read_b128 v[110:113], v64 offset:41568
	v_or_b32_e32 v64, s80, v65
	v_lshlrev_b32_e32 v66, 2, v64
	v_mfma_f32_32x32x16_bf16 v[0:15], v[90:93], v[72:75], v[0:15]
	ds_read_b128 v[72:75], v67 offset:55360
	ds_read_b128 v[90:93], v67 offset:55392
	ds_read_b128 v[114:117], v67 offset:59968
	ds_read_b128 v[118:121], v67 offset:60000
	s_waitcnt lgkmcnt(0)
	s_barrier
	s_barrier
	global_load_dword v64, v66, s[0:1]
	v_or_b32_e32 v66, 0x80, v66
	global_load_dword v66, v66, s[0:1]
	v_mfma_f32_32x32x16_bf16 v[48:63], v[76:79], v[80:83], v[48:63]
	v_and_or_b32 v67, v87, 4, v88
	s_lshl_b32 s0, s14, 1
	s_add_u32 s0, s12, s0
	s_addc_u32 s1, s13, 0
	s_add_u32 s0, s0, 0x4a50000
	s_addc_u32 s1, s1, 0
	v_mfma_f32_32x32x16_bf16 v[32:47], v[94:97], v[80:83], v[32:47]
	v_mfma_f32_32x32x16_bf16 v[16:31], v[76:79], v[98:101], v[16:31]
	v_mfma_f32_32x32x16_bf16 v[0:15], v[94:97], v[98:101], v[0:15]
	v_mfma_f32_32x32x16_bf16 v[48:63], v[68:71], v[72:75], v[48:63]
	v_mfma_f32_32x32x16_bf16 v[32:47], v[106:109], v[72:75], v[32:47]
	v_mfma_f32_32x32x16_bf16 v[16:31], v[68:71], v[114:117], v[16:31]
	v_mfma_f32_32x32x16_bf16 v[0:15], v[106:109], v[114:117], v[0:15]
	v_mfma_f32_32x32x16_bf16 v[48:63], v[102:105], v[90:93], v[48:63]
	v_mfma_f32_32x32x16_bf16 v[32:47], v[110:113], v[90:93], v[32:47]
	s_waitcnt vmcnt(1)
	s_nop 9
	v_mul_f32_e64 v48, v48, v64
	v_mul_f32_e64 v49, v49, v64
	v_mul_f32_e64 v50, v50, v64
	v_mul_f32_e64 v51, v51, v64
	v_cvt_pk_bf16_f32 v48, v48, v49
	v_mfma_f32_32x32x16_bf16 v[16:31], v[102:105], v[118:121], v[16:31]
	v_cvt_pk_bf16_f32 v49, v50, v51
	v_lshlrev_b32_e32 v50, 1, v67
	v_mad_u32_u24 v65, v65, s75, v50
	v_mul_f32_e64 v32, v32, v64
	v_mul_f32_e64 v33, v33, v64
	v_pk_mul_f32 v[34:35], v[34:35], v[64:65] op_sel_hi:[1,0]
	v_pk_mul_f32 v[50:51], v[52:53], v[64:65] op_sel_hi:[1,0]
	v_pk_mul_f32 v[52:53], v[54:55], v[64:65] op_sel_hi:[1,0]
	v_mfma_f32_32x32x16_bf16 v[0:15], v[110:113], v[118:121], v[0:15]
	s_waitcnt vmcnt(0)
	s_nop 1
	v_mul_f32_e64 v16, v16, v66
	v_mul_f32_e64 v17, v17, v66
	v_mul_f32_e64 v18, v18, v66
	v_mul_f32_e64 v19, v19, v66
	v_cvt_pk_bf16_f32 v32, v32, v33
	v_cvt_pk_bf16_f32 v33, v34, v35
	v_pk_mul_f32 v[34:35], v[36:37], v[64:65] op_sel_hi:[1,0]
	v_pk_mul_f32 v[36:37], v[38:39], v[64:65] op_sel_hi:[1,0]
	v_cvt_pk_bf16_f32 v16, v16, v17
	v_pk_mul_f32 v[0:1], v[0:1], v[66:67] op_sel_hi:[1,0]
	v_pk_mul_f32 v[2:3], v[2:3], v[66:67] op_sel_hi:[1,0]
	v_cvt_pk_bf16_f32 v17, v18, v19
	v_pk_mul_f32 v[18:19], v[20:21], v[66:67] op_sel_hi:[1,0]
	v_pk_mul_f32 v[20:21], v[22:23], v[66:67] op_sel_hi:[1,0]
	v_cvt_pk_bf16_f32 v0, v0, v1
	v_cvt_pk_bf16_f32 v1, v2, v3
	v_pk_mul_f32 v[2:3], v[4:5], v[66:67] op_sel_hi:[1,0]
	v_pk_mul_f32 v[4:5], v[6:7], v[66:67] op_sel_hi:[1,0]
	v_cvt_pk_bf16_f32 v50, v50, v51
	v_cvt_pk_bf16_f32 v51, v52, v53
	v_cvt_pk_bf16_f32 v34, v34, v35
	v_cvt_pk_bf16_f32 v35, v36, v37
	v_cvt_pk_bf16_f32 v18, v18, v19
	v_cvt_pk_bf16_f32 v19, v20, v21
	v_add_u32_e32 v22, 0x2000, v65
	v_cvt_pk_bf16_f32 v2, v2, v3
	v_cvt_pk_bf16_f32 v3, v4, v5
	ds_write2_b64 v65, v[48:49], v[50:51] offset1:2
	v_pk_mul_f32 v[48:49], v[56:57], v[64:65] op_sel_hi:[1,0]
	v_pk_mul_f32 v[50:51], v[58:59], v[64:65] op_sel_hi:[1,0]
	ds_write2_b64 v65, v[32:33], v[34:35] offset0:8 offset1:10
	v_pk_mul_f32 v[32:33], v[40:41], v[64:65] op_sel_hi:[1,0]
	v_pk_mul_f32 v[34:35], v[42:43], v[64:65] op_sel_hi:[1,0]
	ds_write2_b64 v22, v[16:17], v[18:19] offset0:64 offset1:66
	v_pk_mul_f32 v[16:17], v[24:25], v[66:67] op_sel_hi:[1,0]
	v_pk_mul_f32 v[18:19], v[26:27], v[66:67] op_sel_hi:[1,0]
	ds_write2_b64 v22, v[0:1], v[2:3] offset0:72 offset1:74
	v_pk_mul_f32 v[0:1], v[8:9], v[66:67] op_sel_hi:[1,0]
	v_pk_mul_f32 v[2:3], v[10:11], v[66:67] op_sel_hi:[1,0]
	v_cvt_pk_bf16_f32 v48, v48, v49
	v_cvt_pk_bf16_f32 v49, v50, v51
	v_pk_mul_f32 v[50:51], v[60:61], v[64:65] op_sel_hi:[1,0]
	v_pk_mul_f32 v[52:53], v[62:63], v[64:65] op_sel_hi:[1,0]
	v_cvt_pk_bf16_f32 v32, v32, v33
	v_cvt_pk_bf16_f32 v33, v34, v35
	v_pk_mul_f32 v[34:35], v[44:45], v[64:65] op_sel_hi:[1,0]
	v_pk_mul_f32 v[36:37], v[46:47], v[64:65] op_sel_hi:[1,0]
	v_cvt_pk_bf16_f32 v16, v16, v17
	v_cvt_pk_bf16_f32 v17, v18, v19
	v_pk_mul_f32 v[18:19], v[28:29], v[66:67] op_sel_hi:[1,0]
	v_pk_mul_f32 v[20:21], v[30:31], v[66:67] op_sel_hi:[1,0]
	v_cvt_pk_bf16_f32 v0, v0, v1
	v_cvt_pk_bf16_f32 v1, v2, v3
	v_pk_mul_f32 v[2:3], v[12:13], v[66:67] op_sel_hi:[1,0]
	v_pk_mul_f32 v[4:5], v[14:15], v[66:67] op_sel_hi:[1,0]
	v_cvt_pk_bf16_f32 v50, v50, v51
	v_cvt_pk_bf16_f32 v51, v52, v53
	v_cvt_pk_bf16_f32 v34, v34, v35
	v_cvt_pk_bf16_f32 v35, v36, v37
	v_cvt_pk_bf16_f32 v18, v18, v19
	v_cvt_pk_bf16_f32 v19, v20, v21
	v_cvt_pk_bf16_f32 v2, v2, v3
	v_cvt_pk_bf16_f32 v3, v4, v5
	ds_write2_b64 v65, v[48:49], v[50:51] offset0:4 offset1:6
	ds_write2_b64 v65, v[32:33], v[34:35] offset0:12 offset1:14
	ds_write2_b64 v22, v[16:17], v[18:19] offset0:68 offset1:70
	ds_write2_b64 v22, v[0:1], v[2:3] offset0:76 offset1:78
	s_waitcnt lgkmcnt(0)
	s_barrier

; __global__ void __launch_bounds__(256, 2) hybrid_megakernel(Params p) {
;     ...
;       const int gi = vb >> 4;
;       int start = 0, mine = 0;
;       for (int g2 = 0; g2 <= gi; ++g2) {
;         const int n = 32 - g2;
;         const int d = (n <= 10) ? 2 : (n <= 22) ? 1 : 0;
;         if (g2 < gi) start += 2 * d; else mine = d;
;       }
;       start += ((vb >> 3) & 1) * mine;
;       const int x = vb & 7;
;       for (int k = 0; k < mine; ++k) { const int slot = start + k; sgu_item(p, l, slot * 8 + x, lds); pool_item(p, l, slot * 8 + x, lds); dilcomb_item(p, x * 64 + slot); }
.LBB0_407:
	s_cmp_ge_u32 s2, 2
	s_cselect_b64 s[4:5], -1, 0
	s_cmp_lt_u32 s2, 30
	v_cndmask_b32_e64 v1, 0, 1, s[4:5]
	s_cselect_b64 vcc, -1, 0
	v_cndmask_b32_e32 v1, 2, v1, vcc
	s_cmp_lt_i32 s2, s0
	v_lshlrev_b32_e32 v2, 1, v1
	s_cselect_b64 vcc, -1, 0
	s_add_i32 s2, s2, 1
	v_cndmask_b32_e32 v2, 0, v2, vcc
	v_cndmask_b32_e32 v116, v1, v116, vcc
	s_cmp_eq_u32 s1, s2
	v_add_u32_e32 v0, v2, v0
	s_cbranch_scc0 .LBB0_407
	v_cmp_gt_i32_e32 vcc, 1, v116
	s_cbranch_vccz .LBB0_410
	s_branch .LBB0_345

; #define LAS __attribute__((address_space(3)))
; __global__ void __launch_bounds__(256, 2) hybrid_megakernel(Params p) {
;   __shared__ __attribute__((aligned(16))) char lds[73728];
;   __shared__ uint4 xb_words;
;   __shared__ uint4 xg_words;
;   cg::grid_group grid = cg::this_grid();
;   char* const ws_ = p.ws;
;   if (p.ws == nullptr) grid.sync();
;   if (threadIdx.x == 0) { xb_words = make_uint4(0u, 0u, 0u, 0u); xg_words = make_uint4(0u, 0u, 0u, 0u); }
;   __syncthreads();
;   const XcdBarrier xb = xcd_barrier_post((unsigned*)(ws_ + OFF_BAR), (volatile LAS unsigned*)&xb_words, gridDim.x);
;   const bool grp = (gridDim.x % 8u) == 0u;
;   const XcdBarrier xg = grp ? xcd_barrier_post((unsigned*)(ws_ + OFF_BAR) + (1 + (blockIdx.x & 7)) * 4096, (volatile LAS unsigned*)&xg_words, gridDim.x / 8u) : xb;
;   const int nb = gridDim.x, bid = blockIdx.x;
;   const int wid = threadIdx.x >> 6;
;   for (int it = bid; it < 3328 + 1024 + 1024 + 32 + 16 + 64; it += nb) {
	.amdhsa_kernel _Z17hybrid_megakernel6Params
		.amdhsa_group_segment_fixed_size 73760
		.amdhsa_private_segment_fixed_size 0
		.amdhsa_kernarg_size 384
		.amdhsa_user_sgpr_count 2
		.amdhsa_user_sgpr_dispatch_ptr 0
		.amdhsa_user_sgpr_queue_ptr 0
		.amdhsa_user_sgpr_kernarg_segment_ptr 1
		.amdhsa_user_sgpr_dispatch_id 0
		.amdhsa_user_sgpr_kernarg_preload_length 0
		.amdhsa_user_sgpr_kernarg_preload_offset 0
		.amdhsa_user_sgpr_private_segment_size 0
		.amdhsa_uses_dynamic_stack 0
		.amdhsa_enable_private_segment 0
		.amdhsa_system_sgpr_workgroup_id_x 1
		.amdhsa_system_sgpr_workgroup_id_y 0
		.amdhsa_system_sgpr_workgroup_id_z 0
		.amdhsa_system_sgpr_workgroup_info 0
		.amdhsa_system_vgpr_workitem_id 2
		.amdhsa_next_free_vgpr 256
		.amdhsa_next_free_sgpr 100
		.amdhsa_accum_offset 256
		.amdhsa_reserve_vcc 1
		.amdhsa_float_round_mode_32 0
		.amdhsa_float_round_mode_16_64 0
		.amdhsa_float_denorm_mode_32 3
		.amdhsa_float_denorm_mode_16_64 3
		.amdhsa_dx10_clamp 1
		.amdhsa_ieee_mode 1
		.amdhsa_fp16_overflow 0
		.amdhsa_tg_split 0
		.amdhsa_exception_fp_ieee_invalid_op 0
		.amdhsa_exception_fp_denorm_src 0
		.amdhsa_exception_fp_ieee_div_zero 0
		.amdhsa_exception_fp_ieee_overflow 0
		.amdhsa_exception_fp_ieee_underflow 0
		.amdhsa_exception_fp_ieee_inexact 0
		.amdhsa_exception_int_div_zero 0
	.end_amdhsa_kernel

; #define LAS __attribute__((address_space(3)))
; __global__ void __launch_bounds__(256, 2) hybrid_megakernel(Params p) {
;   __shared__ __attribute__((aligned(16))) char lds[73728];
;   __shared__ uint4 xb_words;
;   __shared__ uint4 xg_words;
;   cg::grid_group grid = cg::this_grid();
;   char* const ws_ = p.ws;
;   if (p.ws == nullptr) grid.sync();
;   if (threadIdx.x == 0) { xb_words = make_uint4(0u, 0u, 0u, 0u); xg_words = make_uint4(0u, 0u, 0u, 0u); }
;   __syncthreads();
;   const XcdBarrier xb = xcd_barrier_post((unsigned*)(ws_ + OFF_BAR), (volatile LAS unsigned*)&xb_words, gridDim.x);
;   const bool grp = (gridDim.x % 8u) == 0u;
;   const XcdBarrier xg = grp ? xcd_barrier_post((unsigned*)(ws_ + OFF_BAR) + (1 + (blockIdx.x & 7)) * 4096, (volatile LAS unsigned*)&xg_words, gridDim.x / 8u) : xb;
;   const int nb = gridDim.x, bid = blockIdx.x;
;   const int wid = threadIdx.x >> 6;
;   for (int it = bid; it < 3328 + 1024 + 1024 + 32 + 16 + 64; it += nb) {
amdhsa.kernels:
  - .agpr_count:     0
    .args:
      - .offset:         0
        .size:           128
        .value_kind:     by_value
      - .offset:         128
        .size:           4
        .value_kind:     hidden_block_count_x
      - .offset:         132
        .size:           4
        .value_kind:     hidden_block_count_y
      - .offset:         136
        .size:           4
        .value_kind:     hidden_block_count_z
      - .offset:         140
        .size:           2
        .value_kind:     hidden_group_size_x
      - .offset:         142
        .size:           2
        .value_kind:     hidden_group_size_y
      - .offset:         144
        .size:           2
        .value_kind:     hidden_group_size_z
      - .offset:         146
        .size:           2
        .value_kind:     hidden_remainder_x
      - .offset:         148
        .size:           2
        .value_kind:     hidden_remainder_y
      - .offset:         150
        .size:           2
        .value_kind:     hidden_remainder_z
      - .offset:         168
        .size:           8
        .value_kind:     hidden_global_offset_x
      - .offset:         176
        .size:           8
        .value_kind:     hidden_global_offset_y
      - .offset:         184
        .size:           8
        .value_kind:     hidden_global_offset_z
      - .offset:         192
        .size:           2
        .value_kind:     hidden_grid_dims
      - .offset:         216
        .size:           8
        .value_kind:     hidden_multigrid_sync_arg
    .group_segment_fixed_size: 73760
    .kernarg_segment_align: 8
    .kernarg_segment_size: 384
    .language:       OpenCL C
    .language_version:
      - 2
      - 0
    .max_flat_workgroup_size: 256
    .name:           _Z17hybrid_megakernel6Params
    .private_segment_fixed_size: 0
    .sgpr_count:     106
    .sgpr_spill_count: 167
    .symbol:         _Z17hybrid_megakernel6Params.kd
    .uniform_work_group_size: 1
    .uses_dynamic_stack: false
    .vgpr_count:     256
    .vgpr_spill_count: 0
    .wavefront_size: 64
